# adds ev-in/od-in row-scale load batching, RS_FINISH swizzles issued together, rescale-path lgkmcnt drain; otherwise as v8
# baseline (speedup 1.0000x reference)
; __device__ __forceinline__ unsigned cvt_pk_bf16(float lo, float hi) { unsigned r; asm volatile("v_cvt_pk_bf16_f32 %0, %1, %2" : "=v"(r) : "v"(lo), "v"(hi)); return r; }
;     __device__ __forceinline__ void operator()(const f32x4 (&acc)[2][2][4][2], const Unit& u, int wr, int wc, int fr, int fq, const float (&rs)[2][4]) const {
;     ...
;         for (int ai = 0; ai < 2; ++ai)
; #pragma unroll
;             for (int m = 0; m < 4; ++m) { bf16_t* rowp = O + (size_t)(row0 + ai * HALF + m * 16) * FF + col0;
;                 float r[8], e[8]; const float rsv = rs[ai][m]; const float c1 = -rsv * LOG2E, c2 = rsv * rsv;
; #pragma unroll
;                 for (int j = 0; j < 8; ++j) { const float gv = acc[ai][0][m][j >> 2][j & 3], uv = acc[ai][1][m][j >> 2][j & 3]; e[j] = gv * c1; r[j] = gv * uv; }
;                 __builtin_amdgcn_sched_barrier(0);
; #pragma unroll
;                 for (int j = 0; j < 8; ++j) e[j] = __builtin_amdgcn_exp2f(e[j]);
;                 __builtin_amdgcn_sched_barrier(0);
; #pragma unroll
;                 for (int j = 0; j < 8; ++j) e[j] = 1.0f + e[j];
;                 __builtin_amdgcn_sched_barrier(0);
; #pragma unroll
;                 for (int j = 0; j < 8; ++j) e[j] = __builtin_amdgcn_rcpf(e[j]);
;                 __builtin_amdgcn_sched_barrier(0);
; #pragma unroll
;                 for (int j = 0; j < 8; ++j) r[j] = r[j] * (c2 * e[j]);
;                 u32x4 w; w.x = cvt_pk_bf16(r[0], r[1]); w.y = cvt_pk_bf16(r[2], r[3]); w.z = cvt_pk_bf16(r[4], r[5]); w.w = cvt_pk_bf16(r[6], r[7]);
;                 *(u32x4*)rowp = w; }
.LBB0_609:
	s_lshl_b32 s0, s44, 8
	v_mov_b32_e32 v130, v168
	v_mov_b32_e32 v131, v166
	s_add_i32 s0, s0, s74
	s_nop 0
	v_add_u32_e32 v181, s0, v131
	s_lshl_b32 s0, s45, 7
	s_or_b32 s0, s0, s28
	v_lshl_add_u32 v164, v130, 3, s0
	v_ashrrev_i32_e32 v165, 31, v164
	v_lshl_add_u64 v[164:165], v[164:165], 1, s[36:37]
	v_mul_f32_e32 v130, 0xbfb8aa3b, v163
	v_mul_f32_e32 v131, v130, v126
	v_mul_f32_e32 v134, v130, v127
	v_mul_f32_e32 v135, v130, v128
	v_mul_f32_e32 v169, v130, v129
	v_mul_f32_e32 v171, v130, v118
	v_mul_f32_e32 v178, v130, v119
	v_mul_f32_e32 v179, v130, v120
	v_mul_f32_e32 v130, v130, v121
	v_mad_i64_i32 v[176:177], s[0:1], v181, s11, v[164:165]
	v_exp_f32_e32 v131, v131
	v_exp_f32_e32 v134, v134
	v_exp_f32_e32 v135, v135
	v_exp_f32_e32 v169, v169
	v_exp_f32_e32 v171, v171
	v_exp_f32_e32 v178, v178
	v_exp_f32_e32 v179, v179
	v_exp_f32_e32 v130, v130
	v_add_f32_e32 v131, 1.0, v131
	v_add_f32_e32 v134, 1.0, v134
	v_add_f32_e32 v135, 1.0, v135
	v_add_f32_e32 v169, 1.0, v169
	v_add_f32_e32 v171, 1.0, v171
	v_add_f32_e32 v183, 1.0, v178
	v_add_f32_e32 v179, 1.0, v179
	v_add_f32_e32 v130, 1.0, v130
	v_rcp_f32_e32 v178, v131
	v_rcp_f32_e32 v182, v134
	v_rcp_f32_e32 v184, v135
	v_rcp_f32_e32 v186, v169
	v_rcp_f32_e32 v188, v171
	v_rcp_f32_e32 v190, v183
	v_rcp_f32_e32 v192, v179
	v_rcp_f32_e32 v194, v130
	v_pk_mul_f32 v[196:197], v[162:163], v[162:163]
	v_mov_b32_e32 v199, v126
	v_mov_b32_e32 v126, v197
	v_mov_b32_e32 v183, v123
	v_mov_b32_e32 v179, v122
	v_pk_mul_f32 v[122:123], v[126:127], v[182:183]
	v_mov_b32_e32 v185, v124
	v_mul_f32_e32 v126, v122, v123
	v_mov_b32_e32 v122, v197
	v_mov_b32_e32 v123, v128
	v_pk_mul_f32 v[122:123], v[122:123], v[184:185]
	v_mov_b32_e32 v128, v197
	v_mov_b32_e32 v187, v125
	v_mul_f32_e32 v124, v122, v123
	v_pk_mul_f32 v[122:123], v[128:129], v[186:187]
	v_mov_b32_e32 v191, v115
	v_mul_f32_e32 v125, v122, v123
	v_mov_b32_e32 v123, v118
	v_mov_b32_e32 v118, v197
	v_mov_b32_e32 v189, v114
	v_pk_mul_f32 v[114:115], v[118:119], v[190:191]
	v_mov_b32_e32 v193, v116
	v_mul_f32_e32 v118, v114, v115
	v_mov_b32_e32 v114, v197
	v_mov_b32_e32 v115, v120
	v_mov_b32_e32 v198, v197
	v_pk_mul_f32 v[114:115], v[114:115], v[192:193]
	v_mov_b32_e32 v120, v197
	v_mov_b32_e32 v195, v117
	v_pk_mul_f32 v[178:179], v[198:199], v[178:179]
	v_mov_b32_e32 v122, v197
	v_mul_f32_e32 v119, v114, v115
	v_pk_mul_f32 v[114:115], v[120:121], v[194:195]
	v_mul_f32_e32 v130, v178, v179
	v_pk_mul_f32 v[122:123], v[122:123], v[188:189]
	v_mul_f32_e32 v117, v114, v115
	v_cvt_pk_bf16_f32 v114, v130, v126
	v_cvt_pk_bf16_f32 v115, v124, v125
	v_mul_f32_e32 v122, v122, v123
	v_cvt_pk_bf16_f32 v116, v122, v118
	v_cvt_pk_bf16_f32 v117, v119, v117
	global_store_dwordx4 v[176:177], v[114:117], off
	s_nop 1
	v_add_u32_e32 v114, 16, v181
	v_mul_f32_e32 v115, 0xbfb8aa3b, v162
	v_mul_f32_e32 v116, v115, v110
	v_mul_f32_e32 v117, v115, v111
	v_mul_f32_e32 v118, v115, v112
	v_mul_f32_e32 v119, v115, v113
	v_mul_f32_e32 v120, v115, v106
	v_mul_f32_e32 v121, v115, v107
	v_mul_f32_e32 v122, v115, v108
	v_mul_f32_e32 v123, v115, v109
	v_mad_i64_i32 v[114:115], s[0:1], v114, s11, v[164:165]
	v_exp_f32_e32 v116, v116
	v_exp_f32_e32 v117, v117
	v_exp_f32_e32 v118, v118
	v_exp_f32_e32 v119, v119
	v_exp_f32_e32 v120, v120
	v_exp_f32_e32 v121, v121
	v_exp_f32_e32 v122, v122
	v_exp_f32_e32 v123, v123
	v_add_f32_e32 v116, 1.0, v116
	v_add_f32_e32 v117, 1.0, v117
	v_add_f32_e32 v124, 1.0, v118
	v_add_f32_e32 v119, 1.0, v119
	v_add_f32_e32 v125, 1.0, v120
	v_add_f32_e32 v121, 1.0, v121
	v_add_f32_e32 v127, 1.0, v122
	v_add_f32_e32 v123, 1.0, v123
	v_rcp_f32_e32 v162, v123
	v_rcp_f32_e32 v116, v116
	v_rcp_f32_e32 v118, v117
	v_rcp_f32_e32 v120, v124
	v_rcp_f32_e32 v122, v119
	v_rcp_f32_e32 v124, v125
	v_rcp_f32_e32 v126, v121
	v_rcp_f32_e32 v128, v127
	v_mov_b32_e32 v197, v110
	v_mov_b32_e32 v117, v102
	v_pk_mul_f32 v[116:117], v[196:197], v[116:117]
	v_mov_b32_e32 v197, v111
	v_mov_b32_e32 v119, v103
	v_pk_mul_f32 v[102:103], v[196:197], v[118:119]
	v_mov_b32_e32 v197, v112
	v_mov_b32_e32 v121, v104
	v_mul_f32_e32 v111, v102, v103
	v_pk_mul_f32 v[102:103], v[196:197], v[120:121]
	v_mov_b32_e32 v197, v113
	v_mov_b32_e32 v123, v105
	v_mul_f32_e32 v104, v102, v103
	v_pk_mul_f32 v[102:103], v[196:197], v[122:123]
	v_mov_b32_e32 v197, v106
	v_mov_b32_e32 v125, v98
	v_mul_f32_e32 v105, v102, v103
	v_pk_mul_f32 v[102:103], v[196:197], v[124:125]
	v_mov_b32_e32 v197, v107
	v_mov_b32_e32 v127, v99
	v_pk_mul_f32 v[98:99], v[196:197], v[126:127]
	v_mov_b32_e32 v197, v108
	v_mov_b32_e32 v129, v100
	v_mul_f32_e32 v102, v102, v103
	v_mul_f32_e32 v103, v98, v99
	v_pk_mul_f32 v[98:99], v[196:197], v[128:129]
	v_mov_b32_e32 v197, v109
	v_mov_b32_e32 v163, v101
	v_mul_f32_e32 v106, v98, v99
	v_pk_mul_f32 v[98:99], v[196:197], v[162:163]
	v_mul_f32_e32 v110, v116, v117
	v_mul_f32_e32 v101, v98, v99
	v_cvt_pk_bf16_f32 v98, v110, v111
	v_cvt_pk_bf16_f32 v99, v104, v105
	v_cvt_pk_bf16_f32 v100, v102, v103
	v_cvt_pk_bf16_f32 v101, v106, v101
	global_store_dwordx4 v[114:115], v[98:101], off
	s_nop 1
	v_add_u32_e32 v98, 32, v181
	v_mul_f32_e32 v99, 0xbfb8aa3b, v161
	v_mul_f32_e32 v100, v99, v94
	v_mul_f32_e32 v101, v99, v95
	v_mul_f32_e32 v102, v99, v96
	v_mul_f32_e32 v103, v99, v97
	v_mul_f32_e32 v104, v99, v86
	v_mul_f32_e32 v105, v99, v87
	v_mul_f32_e32 v106, v99, v88
	v_mul_f32_e32 v107, v99, v89
	v_mad_i64_i32 v[98:99], s[0:1], v98, s11, v[164:165]
	v_exp_f32_e32 v100, v100
	v_exp_f32_e32 v101, v101
	v_exp_f32_e32 v102, v102
	v_exp_f32_e32 v103, v103
	v_exp_f32_e32 v104, v104
	v_exp_f32_e32 v105, v105
	v_exp_f32_e32 v106, v106
	v_exp_f32_e32 v107, v107
	v_add_f32_e32 v100, 1.0, v100
; __device__ __forceinline__ unsigned cvt_pk_bf16(float lo, float hi) { unsigned r; asm volatile("v_cvt_pk_bf16_f32 %0, %1, %2" : "=v"(r) : "v"(lo), "v"(hi)); return r; }
;     __device__ __forceinline__ void operator()(const f32x4 (&acc)[2][2][4][2], const Unit& u, int wr, int wc, int fr, int fq, const float (&rs)[2][4]) const {
;     ...
;         for (int ai = 0; ai < 2; ++ai)
; #pragma unroll
;             for (int m = 0; m < 4; ++m) { bf16_t* rowp = O + (size_t)(row0 + ai * HALF + m * 16) * FF + col0;
;                 float r[8], e[8]; const float rsv = rs[ai][m]; const float c1 = -rsv * LOG2E, c2 = rsv * rsv;
; #pragma unroll
;                 for (int j = 0; j < 8; ++j) { const float gv = acc[ai][0][m][j >> 2][j & 3], uv = acc[ai][1][m][j >> 2][j & 3]; e[j] = gv * c1; r[j] = gv * uv; }
;                 __builtin_amdgcn_sched_barrier(0);
; #pragma unroll
;                 for (int j = 0; j < 8; ++j) e[j] = __builtin_amdgcn_exp2f(e[j]);
;                 __builtin_amdgcn_sched_barrier(0);
; #pragma unroll
;                 for (int j = 0; j < 8; ++j) e[j] = 1.0f + e[j];
;                 __builtin_amdgcn_sched_barrier(0);
; #pragma unroll
;                 for (int j = 0; j < 8; ++j) e[j] = __builtin_amdgcn_rcpf(e[j]);
;                 __builtin_amdgcn_sched_barrier(0);
; #pragma unroll
;                 for (int j = 0; j < 8; ++j) r[j] = r[j] * (c2 * e[j]);
;                 u32x4 w; w.x = cvt_pk_bf16(r[0], r[1]); w.y = cvt_pk_bf16(r[2], r[3]); w.z = cvt_pk_bf16(r[4], r[5]); w.w = cvt_pk_bf16(r[6], r[7]);
;                 *(u32x4*)rowp = w; }
	v_add_f32_e32 v101, 1.0, v101
	v_add_f32_e32 v108, 1.0, v102
	v_add_f32_e32 v103, 1.0, v103
	v_add_f32_e32 v109, 1.0, v104
	v_add_f32_e32 v105, 1.0, v105
	v_add_f32_e32 v111, 1.0, v106
	v_add_f32_e32 v107, 1.0, v107
	v_rcp_f32_e32 v100, v100
	v_rcp_f32_e32 v102, v101
	v_rcp_f32_e32 v104, v108
	v_rcp_f32_e32 v106, v103
	v_rcp_f32_e32 v108, v109
	v_rcp_f32_e32 v110, v105
	v_rcp_f32_e32 v112, v111
	v_rcp_f32_e32 v114, v107
	v_pk_mul_f32 v[116:117], v[160:161], v[160:161]
	v_mov_b32_e32 v119, v94
	v_mov_b32_e32 v94, v117
	v_mov_b32_e32 v103, v91
	v_mov_b32_e32 v101, v90
	v_pk_mul_f32 v[90:91], v[94:95], v[102:103]
	v_mov_b32_e32 v105, v92
	v_mul_f32_e32 v94, v90, v91
	v_mov_b32_e32 v90, v117
	v_mov_b32_e32 v91, v96
	v_pk_mul_f32 v[90:91], v[90:91], v[104:105]
	v_mov_b32_e32 v96, v117
	v_mov_b32_e32 v107, v93
	v_mul_f32_e32 v92, v90, v91
	v_pk_mul_f32 v[90:91], v[96:97], v[106:107]
	v_mov_b32_e32 v111, v83
	v_mul_f32_e32 v93, v90, v91
	v_mov_b32_e32 v91, v86
	v_mov_b32_e32 v86, v117
	v_mov_b32_e32 v109, v82
	v_pk_mul_f32 v[82:83], v[86:87], v[110:111]
	v_mov_b32_e32 v113, v84
	v_mul_f32_e32 v86, v82, v83
	v_mov_b32_e32 v82, v117
	v_mov_b32_e32 v83, v88
	v_mov_b32_e32 v118, v117
	v_pk_mul_f32 v[82:83], v[82:83], v[112:113]
	v_mov_b32_e32 v88, v117
	v_mov_b32_e32 v115, v85
	v_pk_mul_f32 v[100:101], v[118:119], v[100:101]
	v_mov_b32_e32 v90, v117
	v_mul_f32_e32 v87, v82, v83
	v_pk_mul_f32 v[82:83], v[88:89], v[114:115]
	v_mul_f32_e32 v100, v100, v101
	v_pk_mul_f32 v[90:91], v[90:91], v[108:109]
	v_mul_f32_e32 v85, v82, v83
	v_cvt_pk_bf16_f32 v82, v100, v94
	v_cvt_pk_bf16_f32 v83, v92, v93
	v_mul_f32_e32 v90, v90, v91
	v_cvt_pk_bf16_f32 v84, v90, v86
	v_cvt_pk_bf16_f32 v85, v87, v85
	global_store_dwordx4 v[98:99], v[82:85], off
	s_nop 1
	v_add_u32_e32 v82, 48, v181
	v_mul_f32_e32 v83, 0xbfb8aa3b, v160
	v_mul_f32_e32 v84, v83, v76
	v_mul_f32_e32 v85, v83, v77
	v_mul_f32_e32 v86, v83, v78
	v_mul_f32_e32 v87, v83, v79
	v_mul_f32_e32 v88, v83, v72
	v_mul_f32_e32 v89, v83, v73
	v_mul_f32_e32 v90, v83, v74
	v_mul_f32_e32 v91, v83, v75
	v_mad_i64_i32 v[82:83], s[0:1], v82, s11, v[164:165]
	v_exp_f32_e32 v84, v84
	v_exp_f32_e32 v85, v85
	v_exp_f32_e32 v86, v86
	v_exp_f32_e32 v87, v87
	v_exp_f32_e32 v88, v88
	v_exp_f32_e32 v89, v89
	v_exp_f32_e32 v90, v90
	v_exp_f32_e32 v91, v91
	v_add_f32_e32 v84, 1.0, v84
	v_add_f32_e32 v85, 1.0, v85
	v_add_f32_e32 v92, 1.0, v86
	v_add_f32_e32 v87, 1.0, v87
	v_add_f32_e32 v93, 1.0, v88
	v_add_f32_e32 v89, 1.0, v89
	v_add_f32_e32 v95, 1.0, v90
	v_add_f32_e32 v91, 1.0, v91
	v_rcp_f32_e32 v84, v84
	v_rcp_f32_e32 v86, v85
	v_rcp_f32_e32 v88, v92
	v_rcp_f32_e32 v90, v87
	v_rcp_f32_e32 v92, v93
	v_rcp_f32_e32 v94, v89
	v_rcp_f32_e32 v96, v95
	v_rcp_f32_e32 v98, v91
	v_mov_b32_e32 v117, v76
	v_mov_b32_e32 v85, v68
	v_pk_mul_f32 v[84:85], v[116:117], v[84:85]
	v_mov_b32_e32 v117, v77
	v_mov_b32_e32 v87, v69
	v_pk_mul_f32 v[68:69], v[116:117], v[86:87]
	v_mov_b32_e32 v117, v78
	v_mov_b32_e32 v89, v70
	v_mul_f32_e32 v77, v68, v69
	v_pk_mul_f32 v[68:69], v[116:117], v[88:89]
	v_mov_b32_e32 v117, v79
	v_mov_b32_e32 v91, v71
	v_mul_f32_e32 v70, v68, v69
	v_pk_mul_f32 v[68:69], v[116:117], v[90:91]
	v_mov_b32_e32 v117, v72
	v_mov_b32_e32 v93, v64
	v_mul_f32_e32 v71, v68, v69
	v_pk_mul_f32 v[68:69], v[116:117], v[92:93]
	v_mov_b32_e32 v117, v73
	v_mov_b32_e32 v95, v65
	v_pk_mul_f32 v[64:65], v[116:117], v[94:95]
	v_mov_b32_e32 v117, v74
	v_mov_b32_e32 v97, v66
	v_mul_f32_e32 v68, v68, v69
	v_mul_f32_e32 v69, v64, v65
	v_pk_mul_f32 v[64:65], v[116:117], v[96:97]
	v_mov_b32_e32 v117, v75
	v_mov_b32_e32 v99, v67
	v_mul_f32_e32 v72, v64, v65
	v_pk_mul_f32 v[64:65], v[116:117], v[98:99]
	v_mul_f32_e32 v76, v84, v85
	v_mul_f32_e32 v67, v64, v65
	v_cvt_pk_bf16_f32 v64, v76, v77
	v_cvt_pk_bf16_f32 v65, v70, v71
	v_cvt_pk_bf16_f32 v66, v68, v69
	v_cvt_pk_bf16_f32 v67, v72, v67
	global_store_dwordx4 v[82:83], v[64:67], off
	s_nop 1
	v_add_u32_e32 v64, 0x80, v181
	v_mul_f32_e32 v65, 0xbfb8aa3b, v159
	v_mul_f32_e32 v66, v65, v60
	v_mul_f32_e32 v67, v65, v61
	v_mul_f32_e32 v68, v65, v62
	v_mul_f32_e32 v69, v65, v63
	v_mul_f32_e32 v70, v65, v52
	v_mul_f32_e32 v71, v65, v53
	v_mul_f32_e32 v72, v65, v54
	v_mul_f32_e32 v73, v65, v55
	v_mad_i64_i32 v[64:65], s[0:1], v64, s11, v[164:165]
	v_exp_f32_e32 v66, v66
	v_exp_f32_e32 v67, v67
	v_exp_f32_e32 v68, v68
	v_exp_f32_e32 v69, v69
	v_exp_f32_e32 v70, v70
	v_exp_f32_e32 v71, v71
	v_exp_f32_e32 v72, v72
	v_exp_f32_e32 v73, v73
	v_add_f32_e32 v66, 1.0, v66
	v_add_f32_e32 v67, 1.0, v67
	v_add_f32_e32 v74, 1.0, v68
	v_add_f32_e32 v69, 1.0, v69
	v_add_f32_e32 v75, 1.0, v70
	v_add_f32_e32 v71, 1.0, v71
	v_add_f32_e32 v77, 1.0, v72
	v_add_f32_e32 v73, 1.0, v73
	v_rcp_f32_e32 v66, v66
	v_rcp_f32_e32 v68, v67
	v_rcp_f32_e32 v70, v74
	v_rcp_f32_e32 v72, v69
	v_rcp_f32_e32 v74, v75
	v_rcp_f32_e32 v76, v71
	v_rcp_f32_e32 v78, v77
	v_rcp_f32_e32 v82, v73
	v_pk_mul_f32 v[84:85], v[158:159], v[158:159]
	v_mov_b32_e32 v87, v60
	v_mov_b32_e32 v60, v85
	v_mov_b32_e32 v69, v57
	v_mov_b32_e32 v67, v56
	v_pk_mul_f32 v[56:57], v[60:61], v[68:69]
	v_mov_b32_e32 v71, v58
	v_mul_f32_e32 v60, v56, v57
	v_mov_b32_e32 v56, v85
	v_mov_b32_e32 v57, v62
	v_pk_mul_f32 v[56:57], v[56:57], v[70:71]
	v_mov_b32_e32 v62, v85
	v_mov_b32_e32 v73, v59
	v_mul_f32_e32 v58, v56, v57
	v_pk_mul_f32 v[56:57], v[62:63], v[72:73]
	v_mov_b32_e32 v77, v49
	v_mul_f32_e32 v59, v56, v57
	v_mov_b32_e32 v57, v52
	v_mov_b32_e32 v52, v85
	v_mov_b32_e32 v75, v48
	v_pk_mul_f32 v[48:49], v[52:53], v[76:77]
	v_mov_b32_e32 v79, v50
	v_mul_f32_e32 v52, v48, v49
	v_mov_b32_e32 v48, v85
	v_mov_b32_e32 v49, v54
	v_mov_b32_e32 v86, v85
	v_pk_mul_f32 v[48:49], v[48:49], v[78:79]
; __device__ __forceinline__ unsigned cvt_pk_bf16(float lo, float hi) { unsigned r; asm volatile("v_cvt_pk_bf16_f32 %0, %1, %2" : "=v"(r) : "v"(lo), "v"(hi)); return r; }
; template <class Epi, bool ALIGN_EPI>
; __device__ __forceinline__ void gemm_phase(LAS unsigned char* lds, const Gemm g, const StaticOrder S, const Epi E) {
;     ...
;         E(acc, cur, wr, wc, fr, fq, rs);
;         if (!has_next) break;
;     __device__ __forceinline__ void operator()(const f32x4 (&acc)[2][2][4][2], const Unit& u, int wr, int wc, int fr, int fq, const float (&rs)[2][4]) const {
;     ...
;         for (int ai = 0; ai < 2; ++ai)
; #pragma unroll
;             for (int m = 0; m < 4; ++m) { bf16_t* rowp = O + (size_t)(row0 + ai * HALF + m * 16) * FF + col0;
;                 float r[8], e[8]; const float rsv = rs[ai][m]; const float c1 = -rsv * LOG2E, c2 = rsv * rsv;
; #pragma unroll
;                 for (int j = 0; j < 8; ++j) { const float gv = acc[ai][0][m][j >> 2][j & 3], uv = acc[ai][1][m][j >> 2][j & 3]; e[j] = gv * c1; r[j] = gv * uv; }
;                 __builtin_amdgcn_sched_barrier(0);
; #pragma unroll
;                 for (int j = 0; j < 8; ++j) e[j] = __builtin_amdgcn_exp2f(e[j]);
;                 __builtin_amdgcn_sched_barrier(0);
; #pragma unroll
;                 for (int j = 0; j < 8; ++j) e[j] = 1.0f + e[j];
;                 __builtin_amdgcn_sched_barrier(0);
; #pragma unroll
;                 for (int j = 0; j < 8; ++j) e[j] = __builtin_amdgcn_rcpf(e[j]);
;                 __builtin_amdgcn_sched_barrier(0);
; #pragma unroll
;                 for (int j = 0; j < 8; ++j) r[j] = r[j] * (c2 * e[j]);
;                 u32x4 w; w.x = cvt_pk_bf16(r[0], r[1]); w.y = cvt_pk_bf16(r[2], r[3]); w.z = cvt_pk_bf16(r[4], r[5]); w.w = cvt_pk_bf16(r[6], r[7]);
;                 *(u32x4*)rowp = w; }
	v_mov_b32_e32 v54, v85
	v_mov_b32_e32 v83, v51
	v_pk_mul_f32 v[66:67], v[86:87], v[66:67]
	v_mov_b32_e32 v56, v85
	v_mul_f32_e32 v53, v48, v49
	v_pk_mul_f32 v[48:49], v[54:55], v[82:83]
	v_mul_f32_e32 v66, v66, v67
	v_pk_mul_f32 v[56:57], v[56:57], v[74:75]
	v_mul_f32_e32 v51, v48, v49
	v_cvt_pk_bf16_f32 v48, v66, v60
	v_cvt_pk_bf16_f32 v49, v58, v59
	v_mul_f32_e32 v56, v56, v57
	v_cvt_pk_bf16_f32 v50, v56, v52
	v_cvt_pk_bf16_f32 v51, v53, v51
	global_store_dwordx4 v[64:65], v[48:51], off
	s_nop 1
	v_add_u32_e32 v48, 0x90, v181
	v_mul_f32_e32 v49, 0xbfb8aa3b, v158
	v_mul_f32_e32 v50, v49, v44
	v_mul_f32_e32 v51, v49, v45
	v_mul_f32_e32 v52, v49, v46
	v_mul_f32_e32 v53, v49, v47
	v_mul_f32_e32 v54, v49, v40
	v_mul_f32_e32 v55, v49, v41
	v_mul_f32_e32 v56, v49, v42
	v_mul_f32_e32 v57, v49, v43
	v_mad_i64_i32 v[48:49], s[0:1], v48, s11, v[164:165]
	v_exp_f32_e32 v50, v50
	v_exp_f32_e32 v51, v51
	v_exp_f32_e32 v52, v52
	v_exp_f32_e32 v53, v53
	v_exp_f32_e32 v54, v54
	v_exp_f32_e32 v55, v55
	v_exp_f32_e32 v56, v56
	v_exp_f32_e32 v57, v57
	v_add_f32_e32 v50, 1.0, v50
	v_add_f32_e32 v51, 1.0, v51
	v_add_f32_e32 v58, 1.0, v52
	v_add_f32_e32 v53, 1.0, v53
	v_add_f32_e32 v59, 1.0, v54
	v_add_f32_e32 v55, 1.0, v55
	v_add_f32_e32 v61, 1.0, v56
	v_add_f32_e32 v57, 1.0, v57
	v_rcp_f32_e32 v50, v50
	v_rcp_f32_e32 v52, v51
	v_rcp_f32_e32 v54, v58
	v_rcp_f32_e32 v56, v53
	v_rcp_f32_e32 v58, v59
	v_rcp_f32_e32 v60, v55
	v_rcp_f32_e32 v62, v61
	v_rcp_f32_e32 v64, v57
	v_mov_b32_e32 v85, v44
	v_mov_b32_e32 v51, v36
	v_pk_mul_f32 v[50:51], v[84:85], v[50:51]
	v_mov_b32_e32 v85, v45
	v_mov_b32_e32 v53, v37
	v_pk_mul_f32 v[36:37], v[84:85], v[52:53]
	v_mov_b32_e32 v85, v46
	v_mov_b32_e32 v55, v38
	v_mul_f32_e32 v45, v36, v37
	v_pk_mul_f32 v[36:37], v[84:85], v[54:55]
	v_mov_b32_e32 v85, v47
	v_mov_b32_e32 v57, v39
	v_mul_f32_e32 v38, v36, v37
	v_pk_mul_f32 v[36:37], v[84:85], v[56:57]
	v_mov_b32_e32 v85, v40
	v_mov_b32_e32 v59, v32
	v_mul_f32_e32 v39, v36, v37
	v_pk_mul_f32 v[36:37], v[84:85], v[58:59]
	v_mov_b32_e32 v85, v41
	v_mov_b32_e32 v61, v33
	v_pk_mul_f32 v[32:33], v[84:85], v[60:61]
	v_mov_b32_e32 v85, v42
	v_mov_b32_e32 v63, v34
	v_mul_f32_e32 v36, v36, v37
	v_mul_f32_e32 v37, v32, v33
	v_pk_mul_f32 v[32:33], v[84:85], v[62:63]
	v_mov_b32_e32 v85, v43
	v_mov_b32_e32 v65, v35
	v_mul_f32_e32 v40, v32, v33
	v_pk_mul_f32 v[32:33], v[84:85], v[64:65]
	v_mul_f32_e32 v44, v50, v51
	v_mul_f32_e32 v35, v32, v33
	v_cvt_pk_bf16_f32 v32, v44, v45
	v_cvt_pk_bf16_f32 v33, v38, v39
	v_cvt_pk_bf16_f32 v34, v36, v37
	v_cvt_pk_bf16_f32 v35, v40, v35
	global_store_dwordx4 v[48:49], v[32:35], off
	s_nop 1
	v_add_u32_e32 v32, 0xa0, v181
	v_mul_f32_e32 v33, 0xbfb8aa3b, v157
	v_mul_f32_e32 v34, v33, v28
	v_mul_f32_e32 v35, v33, v29
	v_mul_f32_e32 v36, v33, v30
	v_mul_f32_e32 v37, v33, v31
	v_mul_f32_e32 v38, v33, v20
	v_mul_f32_e32 v39, v33, v21
	v_mul_f32_e32 v40, v33, v22
	v_mul_f32_e32 v41, v33, v23
	v_mad_i64_i32 v[32:33], s[0:1], v32, s11, v[164:165]
	v_exp_f32_e32 v34, v34
	v_exp_f32_e32 v35, v35
	v_exp_f32_e32 v36, v36
	v_exp_f32_e32 v37, v37
	v_exp_f32_e32 v38, v38
	v_exp_f32_e32 v39, v39
	v_exp_f32_e32 v40, v40
	v_exp_f32_e32 v41, v41
	v_add_f32_e32 v34, 1.0, v34
	v_add_f32_e32 v35, 1.0, v35
	v_add_f32_e32 v42, 1.0, v36
	v_add_f32_e32 v37, 1.0, v37
	v_add_f32_e32 v43, 1.0, v38
	v_add_f32_e32 v39, 1.0, v39
	v_add_f32_e32 v45, 1.0, v40
	v_add_f32_e32 v41, 1.0, v41
	v_rcp_f32_e32 v34, v34
	v_rcp_f32_e32 v36, v35
	v_rcp_f32_e32 v38, v42
	v_rcp_f32_e32 v40, v37
	v_rcp_f32_e32 v42, v43
	v_rcp_f32_e32 v44, v39
	v_rcp_f32_e32 v46, v45
	v_rcp_f32_e32 v48, v41
	v_pk_mul_f32 v[50:51], v[156:157], v[156:157]
	v_mov_b32_e32 v53, v28
	v_mov_b32_e32 v28, v51
	v_mov_b32_e32 v37, v25
	v_mov_b32_e32 v35, v24
	v_pk_mul_f32 v[24:25], v[28:29], v[36:37]
	v_mov_b32_e32 v39, v26
	v_mul_f32_e32 v28, v24, v25
	v_mov_b32_e32 v24, v51
	v_mov_b32_e32 v25, v30
	v_pk_mul_f32 v[24:25], v[24:25], v[38:39]
	v_mov_b32_e32 v30, v51
	v_mov_b32_e32 v41, v27
	v_mul_f32_e32 v26, v24, v25
	v_pk_mul_f32 v[24:25], v[30:31], v[40:41]
	v_mov_b32_e32 v45, v17
	v_mul_f32_e32 v27, v24, v25
	v_mov_b32_e32 v25, v20
	v_mov_b32_e32 v20, v51
	v_mov_b32_e32 v43, v16
	v_pk_mul_f32 v[16:17], v[20:21], v[44:45]
	v_mov_b32_e32 v47, v18
	v_mul_f32_e32 v20, v16, v17
	v_mov_b32_e32 v16, v51
	v_mov_b32_e32 v17, v22
	v_mov_b32_e32 v52, v51
	v_pk_mul_f32 v[16:17], v[16:17], v[46:47]
	v_mov_b32_e32 v22, v51
	v_mov_b32_e32 v49, v19
	v_pk_mul_f32 v[34:35], v[52:53], v[34:35]
	v_mov_b32_e32 v24, v51
	v_mul_f32_e32 v21, v16, v17
	v_pk_mul_f32 v[16:17], v[22:23], v[48:49]
	v_mul_f32_e32 v34, v34, v35
	v_pk_mul_f32 v[24:25], v[24:25], v[42:43]
	v_mul_f32_e32 v19, v16, v17
	v_cvt_pk_bf16_f32 v16, v34, v28
	v_cvt_pk_bf16_f32 v17, v26, v27
	v_mul_f32_e32 v24, v24, v25
	v_cvt_pk_bf16_f32 v18, v24, v20
	v_cvt_pk_bf16_f32 v19, v21, v19
	global_store_dwordx4 v[32:33], v[16:19], off
	s_nop 1
	v_add_u32_e32 v16, 0xb0, v181
	v_mul_f32_e32 v17, 0xbfb8aa3b, v156
	v_mul_f32_e32 v18, v17, v12
	v_mul_f32_e32 v19, v17, v13
	v_mul_f32_e32 v20, v17, v14
	v_mul_f32_e32 v21, v17, v15
	v_mul_f32_e32 v22, v17, v8
	v_mul_f32_e32 v23, v17, v9
	v_mul_f32_e32 v24, v17, v10
	v_mul_f32_e32 v25, v17, v11
	v_mad_i64_i32 v[16:17], s[0:1], v16, s11, v[164:165]
	v_exp_f32_e32 v18, v18
	v_exp_f32_e32 v19, v19
	v_exp_f32_e32 v20, v20
	v_exp_f32_e32 v21, v21
	v_exp_f32_e32 v22, v22
	v_exp_f32_e32 v23, v23
	v_exp_f32_e32 v24, v24
	v_exp_f32_e32 v25, v25
	v_add_f32_e32 v18, 1.0, v18
	v_add_f32_e32 v19, 1.0, v19
	v_add_f32_e32 v26, 1.0, v20
	v_add_f32_e32 v21, 1.0, v21
	v_add_f32_e32 v27, 1.0, v22
	v_add_f32_e32 v23, 1.0, v23
	v_add_f32_e32 v29, 1.0, v24
	v_add_f32_e32 v25, 1.0, v25
	v_rcp_f32_e32 v18, v18
	v_rcp_f32_e32 v20, v19
	v_rcp_f32_e32 v22, v26
	v_rcp_f32_e32 v24, v21
	v_rcp_f32_e32 v26, v27
	v_rcp_f32_e32 v28, v23
	v_rcp_f32_e32 v30, v29
	v_rcp_f32_e32 v32, v25
	v_mov_b32_e32 v51, v12
	v_mov_b32_e32 v19, v4
	v_pk_mul_f32 v[18:19], v[50:51], v[18:19]
	v_mov_b32_e32 v51, v13
	v_mov_b32_e32 v21, v5
	v_pk_mul_f32 v[4:5], v[50:51], v[20:21]
	v_mov_b32_e32 v51, v14
	v_mov_b32_e32 v23, v6
	v_mul_f32_e32 v13, v4, v5
	v_pk_mul_f32 v[4:5], v[50:51], v[22:23]
	v_mov_b32_e32 v51, v15
	v_mov_b32_e32 v25, v7
	v_mul_f32_e32 v6, v4, v5
	v_pk_mul_f32 v[4:5], v[50:51], v[24:25]
	v_mov_b32_e32 v51, v8
	v_mov_b32_e32 v27, v0
	v_mul_f32_e32 v7, v4, v5
	v_pk_mul_f32 v[4:5], v[50:51], v[26:27]
	v_mov_b32_e32 v51, v9
	v_mov_b32_e32 v29, v1
	v_pk_mul_f32 v[0:1], v[50:51], v[28:29]
	v_mov_b32_e32 v51, v10
	v_mov_b32_e32 v31, v2
	v_mul_f32_e32 v4, v4, v5
	v_mul_f32_e32 v5, v0, v1
	v_pk_mul_f32 v[0:1], v[50:51], v[30:31]
	v_mov_b32_e32 v51, v11
	v_mov_b32_e32 v33, v3
	v_mul_f32_e32 v8, v0, v1
	v_pk_mul_f32 v[0:1], v[50:51], v[32:33]
	s_and_b64 vcc, exec, s[40:41]
	v_mul_f32_e32 v3, v0, v1
	s_mov_b64 s[40:41], -1
	v_mul_f32_e32 v12, v18, v19
	v_cvt_pk_bf16_f32 v0, v12, v13
	v_cvt_pk_bf16_f32 v1, v6, v7
	v_cvt_pk_bf16_f32 v2, v4, v5
	v_cvt_pk_bf16_f32 v3, v8, v3
	global_store_dwordx4 v[16:17], v[0:3], off
	s_cbranch_vccnz .LBB0_600
; template <int O> __device__ __forceinline__ float swz_xor(float v) { return __builtin_bit_cast(float, __builtin_amdgcn_ds_swizzle(__builtin_bit_cast(int, v), 0x1F | (O << 10))); }
; __device__ __forceinline__ float fq_sum(float v) {
;     v += swz_xor<16>(v);
;     auto rr = __builtin_amdgcn_permlane32_swap(__float_as_uint(v), __float_as_uint(v), false, false);
;     return __uint_as_float(rr[0]) + __uint_as_float(rr[1]);
; }
	s_waitcnt vmcnt(8)
	v_add_f32_e32 v232, v200, v201
	v_add_f32_e32 v233, v202, v203
	v_add_f32_e32 v145, v232, v233
	v_add_f32_e32 v232, v204, v205
	v_add_f32_e32 v233, v206, v207
	v_add_f32_e32 v144, v232, v233
	v_add_f32_e32 v232, v208, v209
	v_add_f32_e32 v233, v210, v211
	v_add_f32_e32 v147, v232, v233
	v_add_f32_e32 v232, v212, v213
	v_add_f32_e32 v233, v214, v215
	v_add_f32_e32 v146, v232, v233
	v_add_f32_e32 v232, v216, v217
	v_add_f32_e32 v233, v218, v219
	v_add_f32_e32 v149, v232, v233
	v_add_f32_e32 v232, v220, v221
	v_add_f32_e32 v233, v222, v223
	v_add_f32_e32 v148, v232, v233
	v_add_f32_e32 v232, v224, v225
	v_add_f32_e32 v233, v226, v227
	v_add_f32_e32 v155, v232, v233
	v_add_f32_e32 v232, v228, v229
	v_add_f32_e32 v233, v230, v231
	v_add_f32_e32 v154, v232, v233
	ds_swizzle_b32 v0, v145 offset:swizzle(SWAP,16)
	ds_swizzle_b32 v2, v144 offset:swizzle(SWAP,16)
	ds_swizzle_b32 v4, v146 offset:swizzle(SWAP,16)
	ds_swizzle_b32 v8, v148 offset:swizzle(SWAP,16)
	ds_swizzle_b32 v10, v154 offset:swizzle(SWAP,16)
	ds_swizzle_b32 v238, v147 offset:swizzle(SWAP,16)
	ds_swizzle_b32 v239, v149 offset:swizzle(SWAP,16)
	ds_swizzle_b32 v240, v155 offset:swizzle(SWAP,16)
	s_waitcnt lgkmcnt(0)
	v_add_f32_e32 v1, v145, v0
	v_add_f32_e32 v0, v144, v2
	v_mov_b32_e32 v3, v1
	v_mov_b32_e32 v2, v0
	s_nop 0
	v_permlane32_swap_b32_e32 v1, v3
	v_permlane32_swap_b32_e32 v0, v2
	v_pk_add_f32 v[0:1], v[0:1], v[2:3]
	s_mov_b32 s0, 0x358637bd
	v_mov_b64_e32 v[6:7], s[0:1]
	v_pk_fma_f32 v[0:1], v[0:1], s[90:91], v[6:7] op_sel_hi:[1,0,0]
	s_andn2_b64 vcc, exec, s[62:63]
	s_waitcnt lgkmcnt(0)
	v_add_f32_e32 v3, v147, v238
	v_add_f32_e32 v2, v146, v4
	v_mov_b32_e32 v5, v3
	v_mov_b32_e32 v4, v2
	s_nop 0
	v_permlane32_swap_b32_e32 v3, v5
	v_permlane32_swap_b32_e32 v2, v4
	v_pk_add_f32 v[2:3], v[2:3], v[4:5]
	v_pk_fma_f32 v[2:3], v[2:3], s[90:91], v[6:7] op_sel_hi:[1,0,0]
	v_cmp_gt_f32_e64 s[40:41], s10, v0
	v_cmp_gt_f32_e64 s[42:43], s10, v1
	v_cmp_gt_f32_e64 s[44:45], s10, v2
	s_waitcnt lgkmcnt(0)
	v_add_f32_e32 v5, v149, v239
	v_add_f32_e32 v4, v148, v8
	v_mov_b32_e32 v9, v5
	v_mov_b32_e32 v8, v4
	s_nop 0
	v_permlane32_swap_b32_e32 v5, v9
	v_permlane32_swap_b32_e32 v4, v8
	v_pk_add_f32 v[4:5], v[4:5], v[8:9]
	v_pk_fma_f32 v[4:5], v[4:5], s[90:91], v[6:7] op_sel_hi:[1,0,0]
	v_cmp_gt_f32_e64 s[48:49], s10, v3
	v_cmp_gt_f32_e64 s[46:47], s10, v4
	v_cmp_gt_f32_e64 s[50:51], s10, v5
	s_waitcnt lgkmcnt(0)
	v_add_f32_e32 v9, v155, v240
	v_add_f32_e32 v8, v154, v10
	v_mov_b32_e32 v11, v9
	v_mov_b32_e32 v10, v8
	s_nop 0
	v_permlane32_swap_b32_e32 v9, v11
	v_permlane32_swap_b32_e32 v8, v10
	v_pk_add_f32 v[8:9], v[8:9], v[10:11]
	s_nop 0
	v_pk_fma_f32 v[6:7], v[8:9], s[90:91], v[6:7] op_sel_hi:[1,0,0]
	s_nop 0
	v_cmp_gt_f32_e64 s[52:53], s10, v6
	v_cmp_gt_f32_e64 s[54:55], s10, v7
	s_cbranch_vccnz .LBB0_599
	s_barrier
	s_branch .LBB0_599

; __device__ __forceinline__ unsigned cvt_pk_bf16(float lo, float hi) { unsigned r; asm volatile("v_cvt_pk_bf16_f32 %0, %1, %2" : "=v"(r) : "v"(lo), "v"(hi)); return r; }
;     __device__ __forceinline__ void operator()(const f32x4 (&acc)[2][2][4][2], const Unit& u, int wr, int wc, int fr, int fq, const float (&rs)[2][4]) const {
;     ...
;             for (int m = 0; m < 4; ++m) { bf16_t* rowp = O + (size_t)(row0 + ai * HALF + m * 16) * ldc + col0;
;                 const float rsv = SCALE ? rs[ai][m] : 1.0f;
; #pragma unroll
;                 for (int bj = 0; bj < 2; ++bj) { const f32x4 v0 = acc[ai][bj][m][0] * rsv, v1 = acc[ai][bj][m][1] * rsv;
;                     u32x4 w; w.x = cvt_pk_bf16(v0[0], v0[1]); w.y = cvt_pk_bf16(v0[2], v0[3]); w.z = cvt_pk_bf16(v1[0], v1[1]); w.w = cvt_pk_bf16(v1[2], v1[3]);
;                     *(u32x4*)(rowp + bj * HALF) = w; } }
.LBB0_856:
	v_cndmask_b32_e64 v130, 0, 1, s[42:43]
	v_cmp_ne_u32_e64 s[44:45], 1, v130
	s_andn2_b64 vcc, exec, s[42:43]
	s_cbranch_vccnz .LBB0_858
	v_lshl_add_u32 v232, s52, 8, v161
	v_ashrrev_i32_e32 v233, 31, v232
	v_lshlrev_b64 v[234:235], 6, v[232:233]
	v_lshl_add_u64 v[234:235], v[142:143], 0, v[234:235]
	v_add_u32_e32 v232, 0x80, v232
	v_ashrrev_i32_e32 v233, 31, v232
	v_lshlrev_b64 v[236:237], 6, v[232:233]
	v_lshl_add_u64 v[236:237], v[142:143], 0, v[236:237]
	global_load_dwordx4 v[200:203], v[234:235], off
	global_load_dwordx4 v[204:207], v[234:235], off offset:1024
	global_load_dwordx4 v[208:211], v[234:235], off offset:2048
	global_load_dwordx4 v[212:215], v[234:235], off offset:3072
	global_load_dwordx4 v[216:219], v[236:237], off
	global_load_dwordx4 v[220:223], v[236:237], off offset:1024
	global_load_dwordx4 v[224:227], v[236:237], off offset:2048
	global_load_dwordx4 v[228:231], v[236:237], off offset:3072
.LBB0_858:
	v_mov_b32_e32 v130, v157
	v_mov_b32_e32 v131, v159
	s_lshl_b32 s0, s54, 8
	s_add_i32 s0, s0, s40
	v_add_u32_e32 v130, s0, v130
	s_lshl_b32 s0, s55, 8
	s_or_b32 s0, s0, s28
	v_lshl_add_u32 v172, v131, 3, s0
	v_ashrrev_i32_e32 v173, 31, v172
	v_lshl_add_u64 v[172:173], v[172:173], 1, s[36:37]
	v_mad_i64_i32 v[176:177], s[0:1], v130, s11, v[172:173]
	v_pk_mul_f32 v[128:129], v[162:163], v[128:129] op_sel_hi:[0,1]
	v_pk_mul_f32 v[126:127], v[162:163], v[126:127] op_sel_hi:[0,1]
	v_pk_mul_f32 v[178:179], v[162:163], v[124:125] op_sel_hi:[0,1]
	v_pk_mul_f32 v[124:125], v[162:163], v[122:123] op_sel_hi:[0,1]
	v_cvt_pk_bf16_f32 v122, v126, v127
	v_cvt_pk_bf16_f32 v123, v128, v129
	v_cvt_pk_bf16_f32 v124, v124, v125
	v_cvt_pk_bf16_f32 v125, v178, v179
	global_store_dwordx4 v[176:177], v[122:125], off
	v_pk_mul_f32 v[118:119], v[162:163], v[118:119] op_sel_hi:[0,1]
	v_pk_mul_f32 v[120:121], v[162:163], v[120:121] op_sel_hi:[0,1]
	v_pk_mul_f32 v[122:123], v[162:163], v[112:113] op_sel_hi:[0,1]
	v_pk_mul_f32 v[112:113], v[162:163], v[110:111] op_sel_hi:[0,1]
	v_cvt_pk_bf16_f32 v110, v118, v119
	v_cvt_pk_bf16_f32 v111, v120, v121
	v_cvt_pk_bf16_f32 v112, v112, v113
	v_cvt_pk_bf16_f32 v113, v122, v123
	global_store_dwordx4 v[176:177], v[110:113], off offset:256
	v_pk_mul_f32 v[114:115], v[156:157], v[114:115] op_sel_hi:[0,1]
	v_pk_mul_f32 v[102:103], v[156:157], v[102:103] op_sel_hi:[0,1]
	v_add_u32_e32 v110, 16, v130
	v_mad_i64_i32 v[110:111], s[0:1], v110, s11, v[172:173]
	v_pk_mul_f32 v[112:113], v[156:157], v[116:117] op_sel_hi:[0,1]
	v_pk_mul_f32 v[116:117], v[156:157], v[108:109] op_sel_hi:[0,1]
	v_pk_mul_f32 v[108:109], v[156:157], v[106:107] op_sel_hi:[0,1]
	v_cvt_pk_bf16_f32 v106, v114, v115
	v_cvt_pk_bf16_f32 v107, v112, v113
	v_cvt_pk_bf16_f32 v108, v108, v109
	v_cvt_pk_bf16_f32 v109, v116, v117
	global_store_dwordx4 v[110:111], v[106:109], off
	v_pk_mul_f32 v[104:105], v[156:157], v[104:105] op_sel_hi:[0,1]
	v_pk_mul_f32 v[98:99], v[164:165], v[98:99] op_sel_hi:[0,1]
	v_pk_mul_f32 v[106:107], v[156:157], v[96:97] op_sel_hi:[0,1]
	v_pk_mul_f32 v[96:97], v[156:157], v[94:95] op_sel_hi:[0,1]
	v_cvt_pk_bf16_f32 v94, v102, v103
	v_cvt_pk_bf16_f32 v95, v104, v105
	v_cvt_pk_bf16_f32 v96, v96, v97
	v_cvt_pk_bf16_f32 v97, v106, v107
	global_store_dwordx4 v[110:111], v[94:97], off offset:256
	v_pk_mul_f32 v[86:87], v[164:165], v[86:87] op_sel_hi:[0,1]
	v_pk_mul_f32 v[88:89], v[164:165], v[88:89] op_sel_hi:[0,1]
	v_add_u32_e32 v94, 32, v130
	v_mad_i64_i32 v[94:95], s[0:1], v94, s11, v[172:173]
	v_pk_mul_f32 v[96:97], v[164:165], v[100:101] op_sel_hi:[0,1]
	v_pk_mul_f32 v[100:101], v[164:165], v[92:93] op_sel_hi:[0,1]
	v_pk_mul_f32 v[92:93], v[164:165], v[90:91] op_sel_hi:[0,1]
	v_cvt_pk_bf16_f32 v90, v98, v99
	v_cvt_pk_bf16_f32 v91, v96, v97
	v_cvt_pk_bf16_f32 v92, v92, v93
	v_cvt_pk_bf16_f32 v93, v100, v101
	global_store_dwordx4 v[94:95], v[90:93], off
	v_pk_mul_f32 v[82:83], v[158:159], v[82:83] op_sel_hi:[0,1]
	v_pk_mul_f32 v[68:69], v[158:159], v[68:69] op_sel_hi:[0,1]
	v_pk_mul_f32 v[90:91], v[164:165], v[78:79] op_sel_hi:[0,1]
	v_pk_mul_f32 v[78:79], v[164:165], v[76:77] op_sel_hi:[0,1]
	v_cvt_pk_bf16_f32 v76, v86, v87
	v_cvt_pk_bf16_f32 v77, v88, v89
	v_cvt_pk_bf16_f32 v78, v78, v79
	v_cvt_pk_bf16_f32 v79, v90, v91
	global_store_dwordx4 v[94:95], v[76:79], off offset:256
	v_pk_mul_f32 v[70:71], v[158:159], v[70:71] op_sel_hi:[0,1]
	v_pk_mul_f32 v[62:63], v[168:169], v[62:63] op_sel_hi:[0,1]
	v_add_u32_e32 v76, 48, v130
	v_mad_i64_i32 v[76:77], s[0:1], v76, s11, v[172:173]
	v_pk_mul_f32 v[78:79], v[158:159], v[84:85] op_sel_hi:[0,1]
	v_pk_mul_f32 v[84:85], v[158:159], v[74:75] op_sel_hi:[0,1]
	v_pk_mul_f32 v[74:75], v[158:159], v[72:73] op_sel_hi:[0,1]
	v_cvt_pk_bf16_f32 v72, v82, v83
	v_cvt_pk_bf16_f32 v73, v78, v79
	v_cvt_pk_bf16_f32 v74, v74, v75
	v_cvt_pk_bf16_f32 v75, v84, v85
	global_store_dwordx4 v[76:77], v[72:75], off
	v_pk_mul_f32 v[60:61], v[168:169], v[60:61] op_sel_hi:[0,1]
	v_pk_mul_f32 v[52:53], v[168:169], v[52:53] op_sel_hi:[0,1]
	v_pk_mul_f32 v[72:73], v[158:159], v[66:67] op_sel_hi:[0,1]
	v_pk_mul_f32 v[66:67], v[158:159], v[64:65] op_sel_hi:[0,1]
	v_cvt_pk_bf16_f32 v64, v68, v69
	v_cvt_pk_bf16_f32 v65, v70, v71
	v_cvt_pk_bf16_f32 v66, v66, v67
	v_cvt_pk_bf16_f32 v67, v72, v73
	global_store_dwordx4 v[76:77], v[64:67], off offset:256
	v_pk_mul_f32 v[54:55], v[168:169], v[54:55] op_sel_hi:[0,1]
	v_pk_mul_f32 v[48:49], v[160:161], v[48:49] op_sel_hi:[0,1]
	v_add_u32_e32 v64, 0x80, v130
	v_mad_i64_i32 v[64:65], s[0:1], v64, s11, v[172:173]
; __device__ __forceinline__ unsigned cvt_pk_bf16(float lo, float hi) { unsigned r; asm volatile("v_cvt_pk_bf16_f32 %0, %1, %2" : "=v"(r) : "v"(lo), "v"(hi)); return r; }
;     __device__ __forceinline__ void operator()(const f32x4 (&acc)[2][2][4][2], const Unit& u, int wr, int wc, int fr, int fq, const float (&rs)[2][4]) const {
;     ...
;             for (int m = 0; m < 4; ++m) { bf16_t* rowp = O + (size_t)(row0 + ai * HALF + m * 16) * ldc + col0;
;                 const float rsv = SCALE ? rs[ai][m] : 1.0f;
; #pragma unroll
;                 for (int bj = 0; bj < 2; ++bj) { const f32x4 v0 = acc[ai][bj][m][0] * rsv, v1 = acc[ai][bj][m][1] * rsv;
;                     u32x4 w; w.x = cvt_pk_bf16(v0[0], v0[1]); w.y = cvt_pk_bf16(v0[2], v0[3]); w.z = cvt_pk_bf16(v1[0], v1[1]); w.w = cvt_pk_bf16(v1[2], v1[3]);
;                     *(u32x4*)(rowp + bj * HALF) = w; } }
	v_pk_mul_f32 v[66:67], v[168:169], v[58:59] op_sel_hi:[0,1]
	v_pk_mul_f32 v[58:59], v[168:169], v[56:57] op_sel_hi:[0,1]
	v_cvt_pk_bf16_f32 v56, v60, v61
	v_cvt_pk_bf16_f32 v57, v62, v63
	v_cvt_pk_bf16_f32 v58, v58, v59
	v_cvt_pk_bf16_f32 v59, v66, v67
	global_store_dwordx4 v[64:65], v[56:59], off
	v_pk_mul_f32 v[36:37], v[160:161], v[36:37] op_sel_hi:[0,1]
	v_pk_mul_f32 v[38:39], v[160:161], v[38:39] op_sel_hi:[0,1]
	v_pk_mul_f32 v[56:57], v[168:169], v[46:47] op_sel_hi:[0,1]
	v_pk_mul_f32 v[46:47], v[168:169], v[44:45] op_sel_hi:[0,1]
	v_cvt_pk_bf16_f32 v44, v52, v53
	v_cvt_pk_bf16_f32 v45, v54, v55
	v_cvt_pk_bf16_f32 v46, v46, v47
	v_cvt_pk_bf16_f32 v47, v56, v57
	global_store_dwordx4 v[64:65], v[44:47], off offset:256
	v_pk_mul_f32 v[32:33], v[170:171], v[32:33] op_sel_hi:[0,1]
	v_pk_mul_f32 v[20:21], v[170:171], v[20:21] op_sel_hi:[0,1]
	v_add_u32_e32 v44, 0x90, v130
	v_mad_i64_i32 v[44:45], s[0:1], v44, s11, v[172:173]
	v_pk_mul_f32 v[46:47], v[160:161], v[50:51] op_sel_hi:[0,1]
	v_pk_mul_f32 v[50:51], v[160:161], v[42:43] op_sel_hi:[0,1]
	v_pk_mul_f32 v[42:43], v[160:161], v[40:41] op_sel_hi:[0,1]
	v_cvt_pk_bf16_f32 v40, v48, v49
	v_cvt_pk_bf16_f32 v41, v46, v47
	v_cvt_pk_bf16_f32 v42, v42, v43
	v_cvt_pk_bf16_f32 v43, v50, v51
	global_store_dwordx4 v[44:45], v[40:43], off
	v_pk_mul_f32 v[22:23], v[170:171], v[22:23] op_sel_hi:[0,1]
	v_pk_mul_f32 v[16:17], v[166:167], v[16:17] op_sel_hi:[0,1]
	v_pk_mul_f32 v[40:41], v[160:161], v[30:31] op_sel_hi:[0,1]
	v_pk_mul_f32 v[30:31], v[160:161], v[28:29] op_sel_hi:[0,1]
	v_cvt_pk_bf16_f32 v28, v36, v37
	v_cvt_pk_bf16_f32 v29, v38, v39
	v_cvt_pk_bf16_f32 v30, v30, v31
	v_cvt_pk_bf16_f32 v31, v40, v41
	global_store_dwordx4 v[44:45], v[28:31], off offset:256
	s_and_b64 vcc, exec, s[44:45]
	s_mov_b64 s[2:3], -1
	v_add_u32_e32 v28, 0xa0, v130
	v_mad_i64_i32 v[28:29], s[0:1], v28, s11, v[172:173]
	v_pk_mul_f32 v[30:31], v[170:171], v[34:35] op_sel_hi:[0,1]
	v_pk_mul_f32 v[34:35], v[170:171], v[26:27] op_sel_hi:[0,1]
	v_pk_mul_f32 v[26:27], v[170:171], v[24:25] op_sel_hi:[0,1]
	v_cvt_pk_bf16_f32 v24, v32, v33
	v_cvt_pk_bf16_f32 v25, v30, v31
	v_cvt_pk_bf16_f32 v26, v26, v27
	v_cvt_pk_bf16_f32 v27, v34, v35
	global_store_dwordx4 v[28:29], v[24:27], off
	v_pk_mul_f32 v[6:7], v[166:167], v[6:7] op_sel_hi:[0,1]
	v_pk_mul_f32 v[4:5], v[166:167], v[4:5] op_sel_hi:[0,1]
	v_pk_mul_f32 v[24:25], v[170:171], v[14:15] op_sel_hi:[0,1]
	v_pk_mul_f32 v[14:15], v[170:171], v[12:13] op_sel_hi:[0,1]
	v_cvt_pk_bf16_f32 v12, v20, v21
	v_cvt_pk_bf16_f32 v13, v22, v23
	v_cvt_pk_bf16_f32 v14, v14, v15
	v_cvt_pk_bf16_f32 v15, v24, v25
	global_store_dwordx4 v[28:29], v[12:15], off offset:256
	s_nop 1
	v_add_u32_e32 v12, 0xb0, v130
	v_mad_i64_i32 v[12:13], s[0:1], v12, s11, v[172:173]
	v_pk_mul_f32 v[14:15], v[166:167], v[18:19] op_sel_hi:[0,1]
	v_pk_mul_f32 v[18:19], v[166:167], v[10:11] op_sel_hi:[0,1]
	v_pk_mul_f32 v[10:11], v[166:167], v[8:9] op_sel_hi:[0,1]
	v_cvt_pk_bf16_f32 v8, v16, v17
	v_cvt_pk_bf16_f32 v9, v14, v15
	v_cvt_pk_bf16_f32 v10, v10, v11
	v_cvt_pk_bf16_f32 v11, v18, v19
	global_store_dwordx4 v[12:13], v[8:11], off
	s_nop 1
	v_pk_mul_f32 v[8:9], v[166:167], v[2:3] op_sel_hi:[0,1]
	v_pk_mul_f32 v[2:3], v[166:167], v[0:1] op_sel_hi:[0,1]
	v_cvt_pk_bf16_f32 v0, v4, v5
	v_cvt_pk_bf16_f32 v1, v6, v7
	v_cvt_pk_bf16_f32 v2, v2, v3
	v_cvt_pk_bf16_f32 v3, v8, v9
	global_store_dwordx4 v[12:13], v[0:3], off offset:256
	s_cbranch_vccnz .LBB0_849
	s_waitcnt vmcnt(16)
	v_add_f32_e32 v232, v200, v201
	v_add_f32_e32 v233, v202, v203
	v_add_f32_e32 v145, v232, v233
	v_add_f32_e32 v232, v204, v205
	v_add_f32_e32 v233, v206, v207
	v_add_f32_e32 v144, v232, v233
	v_add_f32_e32 v232, v208, v209
	v_add_f32_e32 v233, v210, v211
	v_add_f32_e32 v147, v232, v233
	v_add_f32_e32 v232, v212, v213
	v_add_f32_e32 v233, v214, v215
	v_add_f32_e32 v146, v232, v233
	v_add_f32_e32 v232, v216, v217
	v_add_f32_e32 v233, v218, v219
	v_add_f32_e32 v149, v232, v233
	v_add_f32_e32 v232, v220, v221
	v_add_f32_e32 v233, v222, v223
	v_add_f32_e32 v148, v232, v233
	v_add_f32_e32 v232, v224, v225
	v_add_f32_e32 v233, v226, v227
	v_add_f32_e32 v151, v232, v233
	v_add_f32_e32 v232, v228, v229
	v_add_f32_e32 v233, v230, v231
	v_add_f32_e32 v150, v232, v233
	ds_swizzle_b32 v0, v145 offset:swizzle(SWAP,16)
	ds_swizzle_b32 v1, v144 offset:swizzle(SWAP,16)
	ds_swizzle_b32 v2, v147 offset:swizzle(SWAP,16)
	s_andn2_b64 vcc, exec, s[46:47]
	s_waitcnt lgkmcnt(0)
	v_add_f32_e32 v12, v145, v0
	ds_swizzle_b32 v0, v146 offset:swizzle(SWAP,16)
	v_add_f32_e32 v13, v144, v1
	ds_swizzle_b32 v1, v148 offset:swizzle(SWAP,16)
	v_add_f32_e32 v8, v147, v2
	v_mov_b32_e32 v14, v12
	s_waitcnt lgkmcnt(0)
	v_add_f32_e32 v9, v146, v0
	ds_swizzle_b32 v0, v149 offset:swizzle(SWAP,16)
	v_add_f32_e32 v5, v148, v1
	ds_swizzle_b32 v1, v150 offset:swizzle(SWAP,16)
	v_mov_b32_e32 v15, v13
	v_mov_b32_e32 v10, v8
	s_waitcnt lgkmcnt(0)
	v_add_f32_e32 v4, v149, v0
	ds_swizzle_b32 v0, v151 offset:swizzle(SWAP,16)
	v_add_f32_e32 v1, v150, v1
	v_mov_b32_e32 v11, v9
	v_mov_b32_e32 v6, v4
	v_mov_b32_e32 v7, v5
	s_waitcnt lgkmcnt(0)
	v_add_f32_e32 v0, v151, v0
	v_mov_b32_e32 v2, v0
	v_mov_b32_e32 v3, v1
	v_permlane32_swap_b32_e32 v12, v14
	v_permlane32_swap_b32_e32 v13, v15
	v_permlane32_swap_b32_e32 v8, v10
	v_permlane32_swap_b32_e32 v9, v11
	v_permlane32_swap_b32_e32 v4, v6
	v_permlane32_swap_b32_e32 v5, v7
	v_permlane32_swap_b32_e32 v0, v2
	v_permlane32_swap_b32_e32 v1, v3
	s_cbranch_vccnz .LBB0_848
	s_barrier
	s_branch .LBB0_848

; __device__ __forceinline__ unsigned cvt_pk_bf16(float lo, float hi) { unsigned r; asm volatile("v_cvt_pk_bf16_f32 %0, %1, %2" : "=v"(r) : "v"(lo), "v"(hi)); return r; }
;     __device__ __forceinline__ void operator()(const f32x4 (&acc)[2][2][4][2], const Unit& u, int wr, int wc, int fr, int fq, const float (&rs)[2][4]) const {
;     ...
;             for (int m = 0; m < 4; ++m) { bf16_t* rowp = O + (size_t)(row0 + ai * HALF + m * 16) * ldc + col0;
;                 const float rsv = SCALE ? rs[ai][m] : 1.0f;
; #pragma unroll
;                 for (int bj = 0; bj < 2; ++bj) { const f32x4 v0 = acc[ai][bj][m][0] * rsv, v1 = acc[ai][bj][m][1] * rsv;
;                     u32x4 w; w.x = cvt_pk_bf16(v0[0], v0[1]); w.y = cvt_pk_bf16(v0[2], v0[3]); w.z = cvt_pk_bf16(v1[0], v1[1]); w.w = cvt_pk_bf16(v1[2], v1[3]);
;                     *(u32x4*)(rowp + bj * HALF) = w; } }
.LBB0_1558:
	v_cndmask_b32_e64 v130, 0, 1, s[40:41]
	v_cmp_ne_u32_e64 s[42:43], 1, v130
	s_andn2_b64 vcc, exec, s[40:41]
	s_cbranch_vccnz .LBB0_1560
	v_lshl_add_u32 v232, s50, 8, v161
	v_ashrrev_i32_e32 v233, 31, v232
	v_lshlrev_b64 v[234:235], 6, v[232:233]
	v_lshl_add_u64 v[234:235], v[142:143], 0, v[234:235]
	v_add_u32_e32 v232, 0x80, v232
	v_ashrrev_i32_e32 v233, 31, v232
	v_lshlrev_b64 v[236:237], 6, v[232:233]
	v_lshl_add_u64 v[236:237], v[142:143], 0, v[236:237]
	global_load_dwordx4 v[200:203], v[234:235], off
	global_load_dwordx4 v[204:207], v[234:235], off offset:1024
	global_load_dwordx4 v[208:211], v[234:235], off offset:2048
	global_load_dwordx4 v[212:215], v[234:235], off offset:3072
	global_load_dwordx4 v[216:219], v[236:237], off
	global_load_dwordx4 v[220:223], v[236:237], off offset:1024
	global_load_dwordx4 v[224:227], v[236:237], off offset:2048
	global_load_dwordx4 v[228:231], v[236:237], off offset:3072
.LBB0_1560:
	v_mov_b32_e32 v130, v159
	v_mov_b32_e32 v131, v157
	s_lshl_b32 s0, s52, 8
	s_add_i32 s0, s0, s58
	v_add_u32_e32 v131, s0, v131
	s_lshl_b32 s0, s53, 8
	s_or_b32 s0, s0, s28
	v_lshl_add_u32 v172, v130, 3, s0
	v_ashrrev_i32_e32 v173, 31, v172
	v_lshl_add_u64 v[172:173], v[172:173], 1, s[36:37]
	v_mad_i64_i32 v[176:177], s[0:1], v131, s11, v[172:173]
	v_pk_mul_f32 v[128:129], v[162:163], v[128:129] op_sel_hi:[0,1]
	v_pk_mul_f32 v[126:127], v[162:163], v[126:127] op_sel_hi:[0,1]
	v_pk_mul_f32 v[178:179], v[162:163], v[124:125] op_sel_hi:[0,1]
	v_pk_mul_f32 v[124:125], v[162:163], v[122:123] op_sel_hi:[0,1]
	v_cvt_pk_bf16_f32 v122, v126, v127
	v_cvt_pk_bf16_f32 v123, v128, v129
	v_cvt_pk_bf16_f32 v124, v124, v125
	v_cvt_pk_bf16_f32 v125, v178, v179
	global_store_dwordx4 v[176:177], v[122:125], off
	v_pk_mul_f32 v[118:119], v[162:163], v[118:119] op_sel_hi:[0,1]
	v_pk_mul_f32 v[120:121], v[162:163], v[120:121] op_sel_hi:[0,1]
	v_pk_mul_f32 v[122:123], v[162:163], v[112:113] op_sel_hi:[0,1]
	v_pk_mul_f32 v[112:113], v[162:163], v[110:111] op_sel_hi:[0,1]
	v_cvt_pk_bf16_f32 v110, v118, v119
	v_cvt_pk_bf16_f32 v111, v120, v121
	v_cvt_pk_bf16_f32 v112, v112, v113
	v_cvt_pk_bf16_f32 v113, v122, v123
	global_store_dwordx4 v[176:177], v[110:113], off offset:256
	v_pk_mul_f32 v[114:115], v[156:157], v[114:115] op_sel_hi:[0,1]
	v_pk_mul_f32 v[102:103], v[156:157], v[102:103] op_sel_hi:[0,1]
	v_add_u32_e32 v110, 16, v131
	v_mad_i64_i32 v[110:111], s[0:1], v110, s11, v[172:173]
	v_pk_mul_f32 v[112:113], v[156:157], v[116:117] op_sel_hi:[0,1]
	v_pk_mul_f32 v[116:117], v[156:157], v[108:109] op_sel_hi:[0,1]
	v_pk_mul_f32 v[108:109], v[156:157], v[106:107] op_sel_hi:[0,1]
	v_cvt_pk_bf16_f32 v106, v114, v115
	v_cvt_pk_bf16_f32 v107, v112, v113
	v_cvt_pk_bf16_f32 v108, v108, v109
	v_cvt_pk_bf16_f32 v109, v116, v117
	global_store_dwordx4 v[110:111], v[106:109], off
	v_pk_mul_f32 v[104:105], v[156:157], v[104:105] op_sel_hi:[0,1]
	v_pk_mul_f32 v[98:99], v[164:165], v[98:99] op_sel_hi:[0,1]
	v_pk_mul_f32 v[106:107], v[156:157], v[96:97] op_sel_hi:[0,1]
	v_pk_mul_f32 v[96:97], v[156:157], v[94:95] op_sel_hi:[0,1]
	v_cvt_pk_bf16_f32 v94, v102, v103
	v_cvt_pk_bf16_f32 v95, v104, v105
	v_cvt_pk_bf16_f32 v96, v96, v97
	v_cvt_pk_bf16_f32 v97, v106, v107
	global_store_dwordx4 v[110:111], v[94:97], off offset:256
	v_pk_mul_f32 v[86:87], v[164:165], v[86:87] op_sel_hi:[0,1]
	v_pk_mul_f32 v[88:89], v[164:165], v[88:89] op_sel_hi:[0,1]
	v_add_u32_e32 v94, 32, v131
	v_mad_i64_i32 v[94:95], s[0:1], v94, s11, v[172:173]
	v_pk_mul_f32 v[96:97], v[164:165], v[100:101] op_sel_hi:[0,1]
	v_pk_mul_f32 v[100:101], v[164:165], v[92:93] op_sel_hi:[0,1]
	v_pk_mul_f32 v[92:93], v[164:165], v[90:91] op_sel_hi:[0,1]
	v_cvt_pk_bf16_f32 v90, v98, v99
	v_cvt_pk_bf16_f32 v91, v96, v97
	v_cvt_pk_bf16_f32 v92, v92, v93
	v_cvt_pk_bf16_f32 v93, v100, v101
	global_store_dwordx4 v[94:95], v[90:93], off
	v_pk_mul_f32 v[82:83], v[158:159], v[82:83] op_sel_hi:[0,1]
	v_pk_mul_f32 v[68:69], v[158:159], v[68:69] op_sel_hi:[0,1]
	v_pk_mul_f32 v[90:91], v[164:165], v[78:79] op_sel_hi:[0,1]
	v_pk_mul_f32 v[78:79], v[164:165], v[76:77] op_sel_hi:[0,1]
	v_cvt_pk_bf16_f32 v76, v86, v87
	v_cvt_pk_bf16_f32 v77, v88, v89
	v_cvt_pk_bf16_f32 v78, v78, v79
	v_cvt_pk_bf16_f32 v79, v90, v91
	global_store_dwordx4 v[94:95], v[76:79], off offset:256
	v_pk_mul_f32 v[70:71], v[158:159], v[70:71] op_sel_hi:[0,1]
	v_pk_mul_f32 v[62:63], v[168:169], v[62:63] op_sel_hi:[0,1]
	v_add_u32_e32 v76, 48, v131
	v_mad_i64_i32 v[76:77], s[0:1], v76, s11, v[172:173]
	v_pk_mul_f32 v[78:79], v[158:159], v[84:85] op_sel_hi:[0,1]
	v_pk_mul_f32 v[84:85], v[158:159], v[74:75] op_sel_hi:[0,1]
	v_pk_mul_f32 v[74:75], v[158:159], v[72:73] op_sel_hi:[0,1]
	v_cvt_pk_bf16_f32 v72, v82, v83
	v_cvt_pk_bf16_f32 v73, v78, v79
	v_cvt_pk_bf16_f32 v74, v74, v75
	v_cvt_pk_bf16_f32 v75, v84, v85
	global_store_dwordx4 v[76:77], v[72:75], off
	v_pk_mul_f32 v[60:61], v[168:169], v[60:61] op_sel_hi:[0,1]
	v_pk_mul_f32 v[52:53], v[168:169], v[52:53] op_sel_hi:[0,1]
	v_pk_mul_f32 v[72:73], v[158:159], v[66:67] op_sel_hi:[0,1]
	v_pk_mul_f32 v[66:67], v[158:159], v[64:65] op_sel_hi:[0,1]
	v_cvt_pk_bf16_f32 v64, v68, v69
	v_cvt_pk_bf16_f32 v65, v70, v71
	v_cvt_pk_bf16_f32 v66, v66, v67
	v_cvt_pk_bf16_f32 v67, v72, v73
	global_store_dwordx4 v[76:77], v[64:67], off offset:256
	v_pk_mul_f32 v[54:55], v[168:169], v[54:55] op_sel_hi:[0,1]
	v_pk_mul_f32 v[48:49], v[160:161], v[48:49] op_sel_hi:[0,1]
	v_add_u32_e32 v64, 0x80, v131
	v_mad_i64_i32 v[64:65], s[0:1], v64, s11, v[172:173]
; __device__ __forceinline__ unsigned cvt_pk_bf16(float lo, float hi) { unsigned r; asm volatile("v_cvt_pk_bf16_f32 %0, %1, %2" : "=v"(r) : "v"(lo), "v"(hi)); return r; }
;     __device__ __forceinline__ void operator()(const f32x4 (&acc)[2][2][4][2], const Unit& u, int wr, int wc, int fr, int fq, const float (&rs)[2][4]) const {
;     ...
;             for (int m = 0; m < 4; ++m) { bf16_t* rowp = O + (size_t)(row0 + ai * HALF + m * 16) * ldc + col0;
;                 const float rsv = SCALE ? rs[ai][m] : 1.0f;
; #pragma unroll
;                 for (int bj = 0; bj < 2; ++bj) { const f32x4 v0 = acc[ai][bj][m][0] * rsv, v1 = acc[ai][bj][m][1] * rsv;
;                     u32x4 w; w.x = cvt_pk_bf16(v0[0], v0[1]); w.y = cvt_pk_bf16(v0[2], v0[3]); w.z = cvt_pk_bf16(v1[0], v1[1]); w.w = cvt_pk_bf16(v1[2], v1[3]);
;                     *(u32x4*)(rowp + bj * HALF) = w; } }
	v_pk_mul_f32 v[66:67], v[168:169], v[58:59] op_sel_hi:[0,1]
	v_pk_mul_f32 v[58:59], v[168:169], v[56:57] op_sel_hi:[0,1]
	v_cvt_pk_bf16_f32 v56, v60, v61
	v_cvt_pk_bf16_f32 v57, v62, v63
	v_cvt_pk_bf16_f32 v58, v58, v59
	v_cvt_pk_bf16_f32 v59, v66, v67
	global_store_dwordx4 v[64:65], v[56:59], off
	v_pk_mul_f32 v[36:37], v[160:161], v[36:37] op_sel_hi:[0,1]
	v_pk_mul_f32 v[38:39], v[160:161], v[38:39] op_sel_hi:[0,1]
	v_pk_mul_f32 v[56:57], v[168:169], v[46:47] op_sel_hi:[0,1]
	v_pk_mul_f32 v[46:47], v[168:169], v[44:45] op_sel_hi:[0,1]
	v_cvt_pk_bf16_f32 v44, v52, v53
	v_cvt_pk_bf16_f32 v45, v54, v55
	v_cvt_pk_bf16_f32 v46, v46, v47
	v_cvt_pk_bf16_f32 v47, v56, v57
	global_store_dwordx4 v[64:65], v[44:47], off offset:256
	v_pk_mul_f32 v[32:33], v[170:171], v[32:33] op_sel_hi:[0,1]
	v_pk_mul_f32 v[20:21], v[170:171], v[20:21] op_sel_hi:[0,1]
	v_add_u32_e32 v44, 0x90, v131
	v_mad_i64_i32 v[44:45], s[0:1], v44, s11, v[172:173]
	v_pk_mul_f32 v[46:47], v[160:161], v[50:51] op_sel_hi:[0,1]
	v_pk_mul_f32 v[50:51], v[160:161], v[42:43] op_sel_hi:[0,1]
	v_pk_mul_f32 v[42:43], v[160:161], v[40:41] op_sel_hi:[0,1]
	v_cvt_pk_bf16_f32 v40, v48, v49
	v_cvt_pk_bf16_f32 v41, v46, v47
	v_cvt_pk_bf16_f32 v42, v42, v43
	v_cvt_pk_bf16_f32 v43, v50, v51
	global_store_dwordx4 v[44:45], v[40:43], off
	v_pk_mul_f32 v[22:23], v[170:171], v[22:23] op_sel_hi:[0,1]
	v_pk_mul_f32 v[16:17], v[166:167], v[16:17] op_sel_hi:[0,1]
	v_pk_mul_f32 v[40:41], v[160:161], v[30:31] op_sel_hi:[0,1]
	v_pk_mul_f32 v[30:31], v[160:161], v[28:29] op_sel_hi:[0,1]
	v_cvt_pk_bf16_f32 v28, v36, v37
	v_cvt_pk_bf16_f32 v29, v38, v39
	v_cvt_pk_bf16_f32 v30, v30, v31
	v_cvt_pk_bf16_f32 v31, v40, v41
	global_store_dwordx4 v[44:45], v[28:31], off offset:256
	s_and_b64 vcc, exec, s[42:43]
	s_mov_b64 s[2:3], -1
	v_add_u32_e32 v28, 0xa0, v131
	v_mad_i64_i32 v[28:29], s[0:1], v28, s11, v[172:173]
	v_pk_mul_f32 v[30:31], v[170:171], v[34:35] op_sel_hi:[0,1]
	v_pk_mul_f32 v[34:35], v[170:171], v[26:27] op_sel_hi:[0,1]
	v_pk_mul_f32 v[26:27], v[170:171], v[24:25] op_sel_hi:[0,1]
	v_cvt_pk_bf16_f32 v24, v32, v33
	v_cvt_pk_bf16_f32 v25, v30, v31
	v_cvt_pk_bf16_f32 v26, v26, v27
	v_cvt_pk_bf16_f32 v27, v34, v35
	global_store_dwordx4 v[28:29], v[24:27], off
	v_pk_mul_f32 v[6:7], v[166:167], v[6:7] op_sel_hi:[0,1]
	v_pk_mul_f32 v[4:5], v[166:167], v[4:5] op_sel_hi:[0,1]
	v_pk_mul_f32 v[24:25], v[170:171], v[14:15] op_sel_hi:[0,1]
	v_pk_mul_f32 v[14:15], v[170:171], v[12:13] op_sel_hi:[0,1]
	v_cvt_pk_bf16_f32 v12, v20, v21
	v_cvt_pk_bf16_f32 v13, v22, v23
	v_cvt_pk_bf16_f32 v14, v14, v15
	v_cvt_pk_bf16_f32 v15, v24, v25
	global_store_dwordx4 v[28:29], v[12:15], off offset:256
	s_nop 1
	v_add_u32_e32 v12, 0xb0, v131
	v_mad_i64_i32 v[12:13], s[0:1], v12, s11, v[172:173]
	v_pk_mul_f32 v[14:15], v[166:167], v[18:19] op_sel_hi:[0,1]
	v_pk_mul_f32 v[18:19], v[166:167], v[10:11] op_sel_hi:[0,1]
	v_pk_mul_f32 v[10:11], v[166:167], v[8:9] op_sel_hi:[0,1]
	v_cvt_pk_bf16_f32 v8, v16, v17
	v_cvt_pk_bf16_f32 v9, v14, v15
	v_cvt_pk_bf16_f32 v10, v10, v11
	v_cvt_pk_bf16_f32 v11, v18, v19
	global_store_dwordx4 v[12:13], v[8:11], off
	s_nop 1
	v_pk_mul_f32 v[8:9], v[166:167], v[2:3] op_sel_hi:[0,1]
	v_pk_mul_f32 v[2:3], v[166:167], v[0:1] op_sel_hi:[0,1]
	v_cvt_pk_bf16_f32 v0, v4, v5
	v_cvt_pk_bf16_f32 v1, v6, v7
	v_cvt_pk_bf16_f32 v2, v2, v3
	v_cvt_pk_bf16_f32 v3, v8, v9
	global_store_dwordx4 v[12:13], v[0:3], off offset:256
	s_cbranch_vccnz .LBB0_1551
	s_waitcnt vmcnt(16)
	v_add_f32_e32 v232, v200, v201
	v_add_f32_e32 v233, v202, v203
	v_add_f32_e32 v145, v232, v233
	v_add_f32_e32 v232, v204, v205
	v_add_f32_e32 v233, v206, v207
	v_add_f32_e32 v144, v232, v233
	v_add_f32_e32 v232, v208, v209
	v_add_f32_e32 v233, v210, v211
	v_add_f32_e32 v147, v232, v233
	v_add_f32_e32 v232, v212, v213
	v_add_f32_e32 v233, v214, v215
	v_add_f32_e32 v146, v232, v233
	v_add_f32_e32 v232, v216, v217
	v_add_f32_e32 v233, v218, v219
	v_add_f32_e32 v149, v232, v233
	v_add_f32_e32 v232, v220, v221
	v_add_f32_e32 v233, v222, v223
	v_add_f32_e32 v148, v232, v233
	v_add_f32_e32 v232, v224, v225
	v_add_f32_e32 v233, v226, v227
	v_add_f32_e32 v151, v232, v233
	v_add_f32_e32 v232, v228, v229
	v_add_f32_e32 v233, v230, v231
	v_add_f32_e32 v150, v232, v233
	ds_swizzle_b32 v0, v145 offset:swizzle(SWAP,16)
	ds_swizzle_b32 v1, v144 offset:swizzle(SWAP,16)
	ds_swizzle_b32 v2, v147 offset:swizzle(SWAP,16)
	s_andn2_b64 vcc, exec, s[44:45]
	s_waitcnt lgkmcnt(0)
	v_add_f32_e32 v12, v145, v0
	ds_swizzle_b32 v0, v146 offset:swizzle(SWAP,16)
	v_add_f32_e32 v13, v144, v1
	ds_swizzle_b32 v1, v148 offset:swizzle(SWAP,16)
	v_add_f32_e32 v8, v147, v2
	v_mov_b32_e32 v14, v12
	s_waitcnt lgkmcnt(0)
	v_add_f32_e32 v9, v146, v0
	ds_swizzle_b32 v0, v149 offset:swizzle(SWAP,16)
	v_add_f32_e32 v5, v148, v1
	ds_swizzle_b32 v1, v150 offset:swizzle(SWAP,16)
	v_mov_b32_e32 v15, v13
	v_mov_b32_e32 v10, v8
	s_waitcnt lgkmcnt(0)
	v_add_f32_e32 v4, v149, v0
	ds_swizzle_b32 v0, v151 offset:swizzle(SWAP,16)
	v_add_f32_e32 v1, v150, v1
	v_mov_b32_e32 v11, v9
	v_mov_b32_e32 v6, v4
	v_mov_b32_e32 v7, v5
	s_waitcnt lgkmcnt(0)
	v_add_f32_e32 v0, v151, v0
	v_mov_b32_e32 v2, v0
	v_mov_b32_e32 v3, v1
	v_permlane32_swap_b32_e32 v12, v14
	v_permlane32_swap_b32_e32 v13, v15
	v_permlane32_swap_b32_e32 v8, v10
	v_permlane32_swap_b32_e32 v9, v11
	v_permlane32_swap_b32_e32 v4, v6
	v_permlane32_swap_b32_e32 v5, v7
	v_permlane32_swap_b32_e32 v0, v2
	v_permlane32_swap_b32_e32 v1, v3
	s_cbranch_vccnz .LBB0_1550
	s_barrier
	s_branch .LBB0_1550

; #define LAS __attribute__((address_space(3)))
; __device__ __forceinline__ int crow(int r, int hi) { return (r & 3) + 8 * (r >> 2) + 4 * hi; }
; __device__ __forceinline__ float halfmax(float m) { auto rr = __builtin_amdgcn_permlane32_swap(__float_as_uint(m), __float_as_uint(m), false, false); return fmaxf(__uint_as_float(rr[0]), __uint_as_float(rr[1])); }
; #define MX3(a_, b_, c_) __builtin_fmaxf(__builtin_fmaxf((a_), (b_)), (c_))
; template <int MODE> __device__ __forceinline__ void attn_unit(const Unit& a, char* shm) {
;     ...
;             for (int d0 = 0; d0 < ND; ++d0) {
;                 const bf16x8 b0 = *(const LAS bf16x8*)(kp + d0 * 2048), b1 = *(const LAS bf16x8*)(kp + d0 * 2048 + 512);
;                 p0 = __builtin_amdgcn_mfma_f32_32x32x16_bf16(b0, qr[d0], p0, 0, 0, 0);
;                 p1 = __builtin_amdgcn_mfma_f32_32x32x16_bf16(b1, qr[d0], p1, 0, 0, 0);
;             }
;             if (MODE == 1) {
; #pragma unroll
;                 for (int r = 0; r < 16; ++r) { const int ks = 64 * t + crow(r, hi); const int r0 = abs(tq - ks), r1 = abs(tq - ks - 32);
;                     p0[r] = (r0 <= 128) ? p0[r] - a.slope2 * (float)r0 : -INFINITY; p1[r] = (r1 <= 128) ? p1[r] - a.slope2 * (float)r1 : -INFINITY; }
;             }
;     ...
;             float ra = MX3(p0[0], p0[1], p1[0]), rb = MX3(p0[2], p0[3], p1[1]); ra = MX3(ra, p1[2], p1[3]);
; #pragma unroll
;             for (int r = 4; r < 16; r += 4) { ra = MX3(ra, p0[r], p0[r + 1]); rb = MX3(rb, p0[r + 2], p0[r + 3]); ra = MX3(ra, p1[r], p1[r + 1]); rb = MX3(rb, p1[r + 2], p1[r + 3]); }
;     ...
;             float rm = halfmax(__builtin_fmaxf(ra, rb));
;             const bool first = (MODE == 0) && (t == a.t_lo);
;             if (first || __any(rm > THR)) {
;                 const float dl = first ? rm : fmaxf(rm, 0.f);
;                 mhat += dl;
; #pragma unroll
;                 for (int r = 0; r < 16; ++r) { p0[r] -= dl; p1[r] -= dl; negm[r] = -mhat; }
;                 if (!first) {
;                     const float f = __builtin_amdgcn_exp2f(-dl); l_reg *= f;
;                     if (hi == 0) wsf[r32] = f;
; #pragma unroll
;                     for (int r = 0; r < 16; ++r) { const float fr_ = wsf[crow(r, hi)]; o[0][r] *= fr_; o[1][r] *= fr_; }
;                 }
.Lmla_nokpe:
	s_waitcnt lgkmcnt(9)
	v_mfma_f32_32x32x16_bf16 v[48:63], v[190:193], v[86:89], v[48:63]
	s_lshl_b32 s0, s35, 13
	s_add_i32 s1, s0, s48
	s_mov_b32 m0, s1
	s_nop 0
	global_load_lds_dwordx4 v[106:107], off
	s_mov_b32 m0, s12
	s_waitcnt lgkmcnt(8)
	v_mfma_f32_32x32x16_bf16 v[64:79], v[194:197], v[86:89], v[64:79]
	s_waitcnt lgkmcnt(7)
	v_mfma_f32_32x32x16_bf16 v[48:63], v[198:201], v[90:93], v[48:63]
	s_waitcnt lgkmcnt(6)
	v_mfma_f32_32x32x16_bf16 v[64:79], v[202:205], v[90:93], v[64:79]
	s_waitcnt lgkmcnt(5)
	v_mfma_f32_32x32x16_bf16 v[48:63], v[206:209], v[94:97], v[48:63]
	s_waitcnt lgkmcnt(4)
	v_mfma_f32_32x32x16_bf16 v[64:79], v[210:213], v[94:97], v[64:79]
	s_waitcnt lgkmcnt(3)
	v_mfma_f32_32x32x16_bf16 v[48:63], v[214:217], v[98:101], v[48:63]
	s_waitcnt lgkmcnt(2)
	v_mfma_f32_32x32x16_bf16 v[64:79], v[218:221], v[98:101], v[64:79]
	s_waitcnt lgkmcnt(1)
	v_mfma_f32_32x32x16_bf16 v[48:63], v[222:225], v[102:105], v[48:63]
	s_waitcnt lgkmcnt(0)
	v_mfma_f32_32x32x16_bf16 v[64:79], v[226:229], v[102:105], v[64:79]
	s_setprio 0
	ds_read_b64_tr_b16 v[230:231], v149 offset:24576
	ds_read_b64_tr_b16 v[232:233], v149 offset:25088
	ds_read_b64_tr_b16 v[234:235], v149 offset:25600
	ds_read_b64_tr_b16 v[236:237], v149 offset:26112
	ds_read_b64_tr_b16 v[238:239], v149 offset:26624
	ds_read_b64_tr_b16 v[240:241], v149 offset:27136
	ds_read_b64_tr_b16 v[242:243], v149 offset:27648
	ds_read_b64_tr_b16 v[244:245], v149 offset:28160
	ds_read_b64_tr_b16 v[246:247], v149 offset:28672
	ds_read_b64_tr_b16 v[248:249], v149 offset:29184
	ds_read_b64_tr_b16 v[150:151], v149 offset:29696
	ds_read_b64_tr_b16 v[152:153], v149 offset:30208
	ds_read_b64_tr_b16 v[154:155], v149 offset:30720
	ds_read_b64_tr_b16 v[156:157], v149 offset:31232
	v_max_f32_e32 v118, v49, v49
	v_max_f32_e32 v119, v48, v48
	v_max_f32_e32 v118, v119, v118
	v_max3_f32 v114, v50, v51, v65
	v_max3_f32 v115, v118, v64, v66
	v_max3_f32 v115, v115, v67, v52
	v_max3_f32 v114, v114, v54, v55
	v_max3_f32 v115, v115, v53, v68
	v_max3_f32 v114, v114, v70, v71
	v_max3_f32 v115, v115, v69, v56
	v_max3_f32 v114, v114, v58, v59
	v_max3_f32 v115, v115, v57, v72
	v_max3_f32 v114, v114, v74, v75
	v_max3_f32 v115, v115, v73, v60
	v_max3_f32 v114, v114, v62, v63
	v_max3_f32 v115, v115, v61, v76
	v_max3_f32 v114, v114, v78, v79
	v_max3_f32 v114, v115, v77, v114
	v_mov_b32_e32 v115, v114
	s_nop 1
	v_permlane32_swap_b32_e32 v114, v115
	v_max_f32_e32 v115, v115, v115
	v_max_f32_e32 v114, v114, v114
	v_max_f32_e32 v114, v114, v115
	v_cmp_lt_f32_e32 vcc, s19, v114
	s_cbranch_vccz .LBB0_1920
	s_waitcnt lgkmcnt(0)
	v_max_f32_e32 v32, v114, v114
	v_max_f32_e32 v32, 0, v32
	v_exp_f32_e64 v33, -v32
	s_and_saveexec_b64 s[46:47], s[42:43]
	ds_write_b32 v148, v33 offset:49152
	s_or_b64 exec, exec, s[46:47]
	v_pk_add_f32 v[114:115], v[112:113], v[32:33]
	v_pk_mul_f32 v[40:41], v[112:113], v[32:33]
	v_add_u32_e32 v44, s49, v80
	v_pk_add_f32 v[48:49], v[48:49], v[32:33] op_sel_hi:[1,0] neg_lo:[0,1] neg_hi:[0,1]
	v_pk_add_f32 v[64:65], v[64:65], v[32:33] op_sel_hi:[1,0] neg_lo:[0,1] neg_hi:[0,1]
	v_pk_add_f32 v[50:51], v[50:51], v[32:33] op_sel_hi:[1,0] neg_lo:[0,1] neg_hi:[0,1]
	v_pk_add_f32 v[66:67], v[66:67], v[32:33] op_sel_hi:[1,0] neg_lo:[0,1] neg_hi:[0,1]
	v_pk_add_f32 v[52:53], v[52:53], v[32:33] op_sel_hi:[1,0] neg_lo:[0,1] neg_hi:[0,1]
	v_pk_add_f32 v[68:69], v[68:69], v[32:33] op_sel_hi:[1,0] neg_lo:[0,1] neg_hi:[0,1]
	v_pk_add_f32 v[54:55], v[54:55], v[32:33] op_sel_hi:[1,0] neg_lo:[0,1] neg_hi:[0,1]
	v_pk_add_f32 v[70:71], v[70:71], v[32:33] op_sel_hi:[1,0] neg_lo:[0,1] neg_hi:[0,1]
	v_pk_add_f32 v[56:57], v[56:57], v[32:33] op_sel_hi:[1,0] neg_lo:[0,1] neg_hi:[0,1]
	v_pk_add_f32 v[72:73], v[72:73], v[32:33] op_sel_hi:[1,0] neg_lo:[0,1] neg_hi:[0,1]
	v_pk_add_f32 v[58:59], v[58:59], v[32:33] op_sel_hi:[1,0] neg_lo:[0,1] neg_hi:[0,1]
	v_pk_add_f32 v[74:75], v[74:75], v[32:33] op_sel_hi:[1,0] neg_lo:[0,1] neg_hi:[0,1]
	v_pk_add_f32 v[60:61], v[60:61], v[32:33] op_sel_hi:[1,0] neg_lo:[0,1] neg_hi:[0,1]
	v_pk_add_f32 v[76:77], v[76:77], v[32:33] op_sel_hi:[1,0] neg_lo:[0,1] neg_hi:[0,1]
	v_pk_add_f32 v[62:63], v[62:63], v[32:33] op_sel_hi:[1,0] neg_lo:[0,1] neg_hi:[0,1]
	v_pk_add_f32 v[78:79], v[78:79], v[32:33] op_sel_hi:[1,0] neg_lo:[0,1] neg_hi:[0,1]
	ds_read_b128 v[32:35], v44 offset:49216
	ds_read_b128 v[36:39], v44 offset:49248
	v_mov_b32_e32 v115, v41
	ds_read_b128 v[40:43], v44 offset:49152
	ds_read_b128 v[116:119], v44 offset:49184
	v_pk_add_f32 v[46:47], v[114:115], 0 neg_lo:[1,1] neg_hi:[1,1]
	s_waitcnt lgkmcnt(3)
	v_pk_mul_f32 v[26:27], v[26:27], v[34:35]
	s_waitcnt lgkmcnt(2)
	v_pk_mul_f32 v[30:31], v[30:31], v[38:39]
	v_pk_mul_f32 v[28:29], v[28:29], v[36:37]
	v_pk_mul_f32 v[24:25], v[24:25], v[32:33]
	s_waitcnt lgkmcnt(0)
	v_pk_mul_f32 v[22:23], v[22:23], v[118:119]
	v_pk_mul_f32 v[20:21], v[20:21], v[116:117]
	v_pk_mul_f32 v[18:19], v[18:19], v[42:43]
	v_pk_mul_f32 v[16:17], v[16:17], v[40:41]
	v_pk_mul_f32 v[14:15], v[14:15], v[38:39]
	v_pk_mul_f32 v[12:13], v[12:13], v[36:37]
	v_pk_mul_f32 v[10:11], v[10:11], v[34:35]
	v_pk_mul_f32 v[8:9], v[8:9], v[32:33]
	v_pk_mul_f32 v[6:7], v[6:7], v[118:119]
	v_pk_mul_f32 v[4:5], v[4:5], v[116:117]
	v_pk_mul_f32 v[2:3], v[2:3], v[42:43]
	v_pk_mul_f32 v[0:1], v[0:1], v[40:41]
	v_mov_b32_e32 v47, v46
	v_mov_b32_e32 v45, v46
	v_mov_b32_e32 v44, v46
	v_mov_b32_e32 v43, v46
	v_mov_b32_e32 v42, v46
	v_mov_b32_e32 v41, v46
	v_mov_b32_e32 v40, v46
	v_mov_b32_e32 v39, v46
	v_mov_b32_e32 v38, v46
	v_mov_b32_e32 v37, v46
	v_mov_b32_e32 v36, v46
	v_mov_b32_e32 v35, v46
	v_mov_b32_e32 v34, v46
	v_mov_b32_e32 v33, v46
	v_mov_b32_e32 v32, v46
	v_mov_b64_e32 v[112:113], v[114:115]
; __device__ __forceinline__ unsigned cvt_pk_bf16(float lo, float hi) { unsigned r; asm volatile("v_cvt_pk_bf16_f32 %0, %1, %2" : "=v"(r) : "v"(lo), "v"(hi)); return r; }
; template <int MODE> __device__ __forceinline__ void attn_unit(const Unit& a, char* shm) {
;     ...
; #pragma unroll
;             for (int r = 0; r < 16; ++r) { p0[r] = __builtin_amdgcn_exp2f(p0[r]); p1[r] = __builtin_amdgcn_exp2f(p1[r]); }
;             f32x2 s2a = (f32x2){p0[0], p0[1]}, s2b = (f32x2){p1[0], p1[1]};
; #pragma unroll
;             for (int k2 = 1; k2 < 8; ++k2) { s2a += (f32x2){p0[2 * k2], p0[2 * k2 + 1]}; s2b += (f32x2){p1[2 * k2], p1[2 * k2 + 1]}; }
;             s2a += s2b;
;             l_reg += s2a.x + s2a.y;
; #pragma unroll
;             for (int kk = 0; kk < 4; ++kk) { pw[0][kk] = cvt_pk_bf16(p0[2 * kk], p0[2 * kk + 1]); pw[1][kk] = cvt_pk_bf16(p0[8 + 2 * kk], p0[8 + 2 * kk + 1]);
;                 pw[2][kk] = cvt_pk_bf16(p1[2 * kk], p1[2 * kk + 1]); pw[3][kk] = cvt_pk_bf16(p1[8 + 2 * kk], p1[8 + 2 * kk + 1]); }
;             if (g == 0) ATT_PV(pw, sv); else pend = true;
.LBB0_1920:
	v_exp_f32_e32 v128, v48
	v_exp_f32_e32 v122, v64
	v_exp_f32_e32 v129, v49
	v_exp_f32_e32 v123, v65
	v_exp_f32_e32 v140, v50
	v_exp_f32_e32 v138, v66
	v_exp_f32_e32 v141, v51
	v_exp_f32_e32 v139, v67
	v_exp_f32_e32 v136, v52
	v_exp_f32_e32 v126, v68
	v_exp_f32_e32 v137, v53
	v_exp_f32_e32 v127, v69
	v_exp_f32_e32 v124, v54
	v_exp_f32_e32 v120, v70
	v_exp_f32_e32 v125, v55
	v_exp_f32_e32 v121, v71
	v_exp_f32_e32 v118, v56
	v_exp_f32_e32 v116, v72
	v_exp_f32_e32 v119, v57
	v_exp_f32_e32 v117, v73
	v_exp_f32_e32 v114, v58
	v_exp_f32_e32 v72, v74
	v_exp_f32_e32 v115, v59
	v_exp_f32_e32 v73, v75
	v_exp_f32_e32 v70, v60
	v_exp_f32_e32 v68, v76
	v_exp_f32_e32 v71, v61
	v_exp_f32_e32 v69, v77
	v_exp_f32_e32 v66, v62
	v_exp_f32_e32 v64, v78
	v_exp_f32_e32 v67, v63
	v_exp_f32_e32 v65, v79
	ds_read_b64_tr_b16 v[158:159], v149 offset:31744
	ds_read_b64_tr_b16 v[160:161], v149 offset:32256
	s_andn2_b64 vcc, exec, s[44:45]
	v_cvt_pk_bf16_f32 v60, v128, v129
	v_cvt_pk_bf16_f32 v56, v118, v119
	v_cvt_pk_bf16_f32 v52, v122, v123
	v_cvt_pk_bf16_f32 v48, v116, v117
	v_cvt_pk_bf16_f32 v61, v140, v141
	v_cvt_pk_bf16_f32 v57, v114, v115
	v_cvt_pk_bf16_f32 v53, v138, v139
	v_cvt_pk_bf16_f32 v49, v72, v73
	v_cvt_pk_bf16_f32 v62, v136, v137
	v_cvt_pk_bf16_f32 v58, v70, v71
	v_cvt_pk_bf16_f32 v54, v126, v127
	v_cvt_pk_bf16_f32 v50, v68, v69
	v_cvt_pk_bf16_f32 v63, v124, v125
	v_cvt_pk_bf16_f32 v59, v66, v67
	v_cvt_pk_bf16_f32 v55, v120, v121
	v_cvt_pk_bf16_f32 v51, v64, v65
	s_cbranch_vccnz .LBB0_1922
	s_waitcnt lgkmcnt(0)
	v_mfma_f32_32x32x16_bf16 v[0:15], v[60:63], v[230:233], v[0:15]
	v_pk_add_f32 v[74:75], v[128:129], v[140:141]
	v_pk_add_f32 v[76:77], v[122:123], v[138:139]
	v_mfma_f32_32x32x16_bf16 v[0:15], v[56:59], v[234:237], v[0:15]
	v_pk_add_f32 v[74:75], v[136:137], v[74:75]
	v_pk_add_f32 v[76:77], v[126:127], v[76:77]
	v_mfma_f32_32x32x16_bf16 v[0:15], v[52:55], v[238:241], v[0:15]
	v_pk_add_f32 v[74:75], v[124:125], v[74:75]
	v_pk_add_f32 v[76:77], v[120:121], v[76:77]
	v_mfma_f32_32x32x16_bf16 v[0:15], v[48:51], v[242:245], v[0:15]
	v_pk_add_f32 v[74:75], v[118:119], v[74:75]
	v_pk_add_f32 v[76:77], v[116:117], v[76:77]
	v_mfma_f32_32x32x16_bf16 v[16:31], v[60:63], v[246:249], v[16:31]
	v_pk_add_f32 v[74:75], v[114:115], v[74:75]
	v_pk_add_f32 v[72:73], v[72:73], v[76:77]
	v_mfma_f32_32x32x16_bf16 v[16:31], v[56:59], v[150:153], v[16:31]
	v_pk_add_f32 v[70:71], v[70:71], v[74:75]
	v_pk_add_f32 v[68:69], v[68:69], v[72:73]
	v_mfma_f32_32x32x16_bf16 v[16:31], v[52:55], v[154:157], v[16:31]
	v_pk_add_f32 v[66:67], v[66:67], v[70:71]
	v_pk_add_f32 v[64:65], v[64:65], v[68:69]
	v_mfma_f32_32x32x16_bf16 v[16:31], v[48:51], v[158:161], v[16:31]
	v_pk_add_f32 v[64:65], v[64:65], v[66:67]
	v_pk_add_f32 v[64:65], v[64:65], v[64:65] op_sel:[0,1] op_sel_hi:[1,0]
	v_pk_add_f32 v[64:65], v[112:113], v[64:65] op_sel:[1,0] op_sel_hi:[0,1]
	s_branch .Lmla_sumdone
